# P2 GEMM: per-unit vmcnt(0) moved to loop entry; first two K-loop waits of a unit count the epilogue stores (vmcnt 8+S)
# baseline (speedup 1.0000x reference)
.LBB0_250:
	s_add_u32 s80, s12, 0x5000000
	s_addc_u32 s81, s13, 0
	s_add_u32 s18, s12, 0x8000000
	s_addc_u32 s19, s13, 0
	s_add_u32 s82, s12, 0xa000000
	s_mov_b64 s[24:25], 0x80
	s_addc_u32 s83, s13, 0
	s_and_b32 s84, s1, 3
	s_add_i32 m0, s76, 0x18000
	v_lshl_add_u64 v[8:9], v[8:9], 0, s[24:25]
	s_lshl_b32 s85, s2, 6
	s_lshl_b32 s1, s2, 13
	s_lshl_b32 s2, s84, 12
	s_waitcnt vmcnt(2)
	s_barrier
	global_load_lds_dwordx4 v[8:9], off
	v_lshl_add_u64 v[6:7], v[6:7], 0, s[24:25]
	s_add_i32 m0, s76, 0x1a000
	s_add_i32 s86, s76, 0x8000
	s_add_i32 s87, s76, 0xa000
	global_load_lds_dwordx4 v[6:7], off
	v_lshl_add_u64 v[2:3], v[2:3], 0, s[24:25]
	s_mov_b32 m0, s86
	s_add_u32 s26, s60, 0x40080
	global_load_lds_dwordx4 v[2:3], off
	v_lshl_add_u64 v[2:3], v[4:5], 0, s[24:25]
	s_mov_b32 m0, s87
	s_addc_u32 s27, s61, 0
	global_load_lds_dwordx4 v[2:3], off
	s_add_i32 m0, s76, 0x1c000
	v_lshl_add_u64 v[2:3], s[26:27], 0, v[148:149]
	global_load_lds_dwordx4 v[2:3], off
	v_lshl_add_u64 v[2:3], s[26:27], 0, v[152:153]
	s_add_i32 m0, s76, 0x1e000
	v_and_b32_e32 v1, 15, v0
	global_load_lds_dwordx4 v[2:3], off
	v_bfe_u32 v14, v0, 4, 2
	s_cmpk_lt_u32 s0, 0x100
	v_lshlrev_b32_e32 v154, 4, v14
	v_lshlrev_b32_e32 v15, 6, v1
	s_cselect_b64 s[26:27], -1, 0
	s_cmp_gt_u32 s84, 1
	v_or_b32_e32 v2, v15, v154
	v_and_b32_e32 v3, 32, v239
	s_cselect_b64 s[36:37], -1, 0
	s_add_i32 s0, 0, 0x20000
	v_bitop3_b32 v6, v2, s1, v3 bitop3:0xde
	v_lshlrev_b32_e32 v2, 6, v0
	s_movk_i32 s1, 0x3c0
	v_add_u32_e32 v172, s0, v154
	s_add_i32 s0, 0, 0x21000
	v_and_or_b32 v2, v2, s1, v154
	s_lshl_b32 s88, s84, 6
	v_add_u32_e32 v173, s0, v154
	s_lshl_b32 s0, s84, 7
	s_ashr_i32 s89, s3, 31
	s_ashr_i32 s90, s97, 31
	v_bitop3_b32 v157, s2, v2, v3 bitop3:0xf6
	s_add_u32 s0, s12, s0
	v_or_b32_e32 v3, 0x400, v15
	s_addc_u32 s1, s13, 0
	v_add_u32_e32 v176, v172, v3
	v_add_u32_e32 v177, v173, v3
	v_or_b32_e32 v3, 0x800, v15
	s_add_u32 s91, s0, 0x7000000
	v_add_u32_e32 v178, v172, v3
	v_add_u32_e32 v179, v173, v3
	v_or_b32_e32 v3, 0xc00, v15
	s_addc_u32 s92, s1, 0
	v_add_u32_e32 v180, v172, v3
	v_add_u32_e32 v181, v173, v3
	v_lshl_add_u64 v[4:5], s[0:1], 0, v[154:155]
	s_mov_b64 s[0:1], 0x7800000
	v_lshlrev_b32_e32 v3, 8, v0
	v_lshl_add_u64 v[158:159], v[4:5], 0, s[0:1]
	v_and_b32_e32 v3, 0x18000, v3
	v_lshlrev_b32_e32 v4, 11, v12
	v_or3_b32 v3, v10, v3, v4
	v_add_u32_e32 v160, v3, v11
	v_lshlrev_b32_e32 v3, 4, v13
	s_waitcnt vmcnt(6)
	v_lshlrev_b32_e32 v2, 2, v14
	v_and_b32_e32 v3, 0x38000, v3
	v_lshlrev_b32_e32 v156, 3, v14
	v_or3_b32 v3, v10, v3, v4
	s_add_i32 s94, 0, 0x10000
	s_add_i32 s95, 0, 0x14000
	v_lshlrev_b32_e32 v185, 2, v2
	v_mbcnt_lo_u32_b32 v2, -1, 0
	v_add_u32_e32 v174, v172, v15
	v_add_u32_e32 v175, v173, v15
	v_mov_b32_e32 v161, v155
	v_add_u32_e32 v162, v3, v11
	v_mov_b32_e32 v163, v155
	s_movk_i32 s93, 0xe1
	v_add_u32_e32 v182, s94, v157
	v_add_u32_e32 v183, s95, v157
	v_add_u32_e32 v184, 0, v6
	v_lshlrev_b32_e32 v164, 1, v156
	v_mov_b32_e32 v186, 0x358637bd
	s_mov_b32 s96, 0xf800000
	v_mov_b32_e32 v187, 0x260
	s_mov_b64 s[38:39], 0x8000
	s_mov_b64 s[40:41], 0x9000
	s_mov_b64 s[42:43], 0xa000
	s_mov_b64 s[44:45], 0xaf00
	s_movk_i32 s64, 0x200
	s_mov_b32 s65, 0x10800000
	s_mov_b32 s46, 0xbfb8aa3b
	v_mov_b64_e32 v[166:167], 0x6ff
	v_mov_b32_e32 v188, 0x3e38aa3b
	v_mbcnt_hi_u32_b32 v189, -1, v2
	s_mov_b32 s34, 0
	s_barrier
	s_waitcnt vmcnt(0)
	s_mov_b32 s98, 0
	s_branch .LBB0_253

.LBB0_256:
	s_ashr_i32 s51, s50, 31
	s_lshl_b64 s[0:1], s[50:51], 19
	s_add_u32 s54, s69, s0
	s_addc_u32 s55, s74, s1
	s_and_b64 s[0:1], s[52:53], exec
	s_cselect_b32 s0, s55, s59
	s_cselect_b32 s1, s54, s58
	s_ashr_i32 s49, s48, 31
	s_lshl_b64 s[28:29], s[48:49], 19
	s_add_u32 s56, s47, s28
	s_addc_u32 s57, s68, s29
	s_and_b64 s[28:29], s[52:53], exec
	s_cselect_b32 s2, s57, s61
	s_cselect_b32 s5, s56, s60
	s_add_u32 s58, s58, 0x40080
	s_addc_u32 s59, s59, 0
	s_add_u32 s7, s60, 0x100
	v_mov_b32_e32 v2, 0
	s_addc_u32 s14, s61, 0
	s_mov_b32 s28, -2
	v_mov_b32_e32 v3, v2
	v_mov_b32_e32 v4, v2
	v_mov_b32_e32 v5, v2
	v_mov_b32_e32 v6, v2
	v_mov_b32_e32 v7, v2
	v_mov_b32_e32 v8, v2
	v_mov_b32_e32 v9, v2
	v_mov_b32_e32 v18, v2
	v_mov_b32_e32 v19, v2
	v_mov_b32_e32 v20, v2
	v_mov_b32_e32 v21, v2
	v_mov_b32_e32 v22, v2
	v_mov_b32_e32 v23, v2
	v_mov_b32_e32 v24, v2
	v_mov_b32_e32 v25, v2
	v_mov_b32_e32 v34, v2
	v_mov_b32_e32 v35, v2
	v_mov_b32_e32 v36, v2
	v_mov_b32_e32 v37, v2
	v_mov_b32_e32 v38, v2
	v_mov_b32_e32 v39, v2
	v_mov_b32_e32 v40, v2
	v_mov_b32_e32 v41, v2
	v_mov_b32_e32 v50, v2
	v_mov_b32_e32 v51, v2
	v_mov_b32_e32 v52, v2
	v_mov_b32_e32 v53, v2
	v_mov_b32_e32 v54, v2
	v_mov_b32_e32 v55, v2
	v_mov_b32_e32 v56, v2
	v_mov_b32_e32 v57, v2
	v_mov_b32_e32 v10, v2
	v_mov_b32_e32 v11, v2
	v_mov_b32_e32 v12, v2
	v_mov_b32_e32 v13, v2
	v_mov_b32_e32 v14, v2
	v_mov_b32_e32 v15, v2
	v_mov_b32_e32 v16, v2
	v_mov_b32_e32 v17, v2
	v_mov_b32_e32 v26, v2
	v_mov_b32_e32 v27, v2
	v_mov_b32_e32 v28, v2
	v_mov_b32_e32 v29, v2
	v_mov_b32_e32 v30, v2
	v_mov_b32_e32 v31, v2
	v_mov_b32_e32 v32, v2
	v_mov_b32_e32 v33, v2
	v_mov_b32_e32 v42, v2
	v_mov_b32_e32 v43, v2
	v_mov_b32_e32 v44, v2
	v_mov_b32_e32 v45, v2
	v_mov_b32_e32 v46, v2
	v_mov_b32_e32 v47, v2
	v_mov_b32_e32 v48, v2
	v_mov_b32_e32 v49, v2
	v_mov_b32_e32 v58, v2
	v_mov_b32_e32 v59, v2
	v_mov_b32_e32 v60, v2
	v_mov_b32_e32 v61, v2
	v_mov_b32_e32 v62, v2
	v_mov_b32_e32 v63, v2
	v_mov_b32_e32 v64, v2
	v_mov_b32_e32 v65, v2
	v_mov_b32_e32 v66, v2
	v_mov_b32_e32 v67, v2
	v_mov_b32_e32 v68, v2
	v_mov_b32_e32 v69, v2
	v_mov_b32_e32 v70, v2
	v_mov_b32_e32 v71, v2
	v_mov_b32_e32 v72, v2
	v_mov_b32_e32 v73, v2
	v_mov_b32_e32 v82, v2
	v_mov_b32_e32 v83, v2
	v_mov_b32_e32 v84, v2
	v_mov_b32_e32 v85, v2
	v_mov_b32_e32 v86, v2
	v_mov_b32_e32 v87, v2
	v_mov_b32_e32 v88, v2
	v_mov_b32_e32 v89, v2
	v_mov_b32_e32 v98, v2
	v_mov_b32_e32 v99, v2
	v_mov_b32_e32 v100, v2
	v_mov_b32_e32 v101, v2
	v_mov_b32_e32 v102, v2
	v_mov_b32_e32 v103, v2
	v_mov_b32_e32 v104, v2
	v_mov_b32_e32 v105, v2
	v_mov_b32_e32 v114, v2
	v_mov_b32_e32 v115, v2
	v_mov_b32_e32 v116, v2
	v_mov_b32_e32 v117, v2
	v_mov_b32_e32 v118, v2
	v_mov_b32_e32 v119, v2
	v_mov_b32_e32 v120, v2
	v_mov_b32_e32 v121, v2
	v_mov_b32_e32 v74, v2
	v_mov_b32_e32 v75, v2
	v_mov_b32_e32 v76, v2
	v_mov_b32_e32 v77, v2
	v_mov_b32_e32 v78, v2
	v_mov_b32_e32 v79, v2
	v_mov_b32_e32 v80, v2
	v_mov_b32_e32 v81, v2
	v_mov_b32_e32 v90, v2
	v_mov_b32_e32 v91, v2
	v_mov_b32_e32 v92, v2
	v_mov_b32_e32 v93, v2
	v_mov_b32_e32 v94, v2
	v_mov_b32_e32 v95, v2
	v_mov_b32_e32 v96, v2
	v_mov_b32_e32 v97, v2
	v_mov_b32_e32 v106, v2
	v_mov_b32_e32 v107, v2
	v_mov_b32_e32 v108, v2
	v_mov_b32_e32 v109, v2
	v_mov_b32_e32 v110, v2
	v_mov_b32_e32 v111, v2
	v_mov_b32_e32 v112, v2
	v_mov_b32_e32 v113, v2
	v_mov_b32_e32 v122, v2
	v_mov_b32_e32 v123, v2
	v_mov_b32_e32 v124, v2
	v_mov_b32_e32 v125, v2
	v_mov_b32_e32 v126, v2
	v_mov_b32_e32 v127, v2
	v_mov_b32_e32 v128, v2
	v_mov_b32_e32 v129, v2
.LBB0_257:
	ds_read_b128 v[130:133], v182
	ds_read_b128 v[134:137], v182 offset:1024
	ds_read_b128 v[138:141], v182 offset:2048
	ds_read_b128 v[142:145], v182 offset:3072
	ds_read_b128 v[168:171], v183
	ds_read_b128 v[190:193], v183 offset:1024
	ds_read_b128 v[194:197], v183 offset:2048
	ds_read_b128 v[198:201], v183 offset:3072
	s_add_u32 s29, s58, 0xfffc0080
	s_addc_u32 s30, s59, -1
	s_cmp_eq_u32 s28, 12
	s_cselect_b32 s63, s0, s30
	s_cselect_b32 s62, s1, s29
	s_cselect_b32 s61, s2, s14
	s_cselect_b32 s60, s5, s7
	v_lshl_add_u64 v[222:223], s[58:59], 0, v[160:161]
	s_add_i32 m0, s76, 0xc000
	ds_read_b128 v[202:205], v184
	ds_read_b128 v[206:209], v184 offset:1024
	ds_read_b128 v[210:213], v184 offset:2048
	ds_read_b128 v[214:217], v184 offset:3072
	ds_read_b128 v[218:221], v184 offset:4096
	ds_read_b128 v[226:229], v184 offset:5120
	ds_read_b128 v[230:233], v184 offset:6144
	ds_read_b128 v[234:237], v184 offset:7168
	global_load_lds_dwordx4 v[222:223], off
	v_lshl_add_u64 v[222:223], s[58:59], 0, v[162:163]
	s_add_i32 m0, s76, 0xe000
	s_nop 0
	global_load_lds_dwordx4 v[222:223], off
	s_cmp_lg_u32 s98, 1
	s_cbranch_scc1 .Lp2w_s1_b
	s_waitcnt vmcnt(24)
	s_branch .Lp2w_s1_j
.Lp2w_s1_b:
	s_cmp_lg_u32 s98, 2
	s_cbranch_scc1 .Lp2w_s1_c
	s_waitcnt vmcnt(16)
	s_branch .Lp2w_s1_j
.Lp2w_s1_c:
	s_waitcnt vmcnt(8)
.Lp2w_s1_j:
	s_waitcnt lgkmcnt(0)
	s_barrier
	s_setprio 1
	s_waitcnt lgkmcnt(0)
	v_mfma_f32_16x16x32_bf16 v[126:129], v[130:133], v[202:205], v[126:129]
	v_mfma_f32_16x16x32_bf16 v[122:125], v[138:141], v[202:205], v[122:125]
	v_mfma_f32_16x16x32_bf16 v[110:113], v[130:133], v[210:213], v[110:113]
	v_mfma_f32_16x16x32_bf16 v[106:109], v[138:141], v[210:213], v[106:109]
	v_mfma_f32_16x16x32_bf16 v[94:97], v[130:133], v[218:221], v[94:97]
	v_mfma_f32_16x16x32_bf16 v[90:93], v[138:141], v[218:221], v[90:93]
	v_mfma_f32_16x16x32_bf16 v[78:81], v[130:133], v[230:233], v[78:81]
	v_mfma_f32_16x16x32_bf16 v[74:77], v[138:141], v[230:233], v[74:77]
	v_mfma_f32_16x16x32_bf16 v[126:129], v[134:137], v[206:209], v[126:129]
	v_mfma_f32_16x16x32_bf16 v[122:125], v[142:145], v[206:209], v[122:125]
	v_mfma_f32_16x16x32_bf16 v[110:113], v[134:137], v[214:217], v[110:113]
	v_mfma_f32_16x16x32_bf16 v[106:109], v[142:145], v[214:217], v[106:109]
	v_mfma_f32_16x16x32_bf16 v[94:97], v[134:137], v[226:229], v[94:97]
	v_mfma_f32_16x16x32_bf16 v[90:93], v[142:145], v[226:229], v[90:93]
	v_mfma_f32_16x16x32_bf16 v[78:81], v[134:137], v[234:237], v[78:81]
	v_mfma_f32_16x16x32_bf16 v[74:77], v[142:145], v[234:237], v[74:77]
	s_setprio 0
	s_setprio 1
	v_mfma_f32_16x16x32_bf16 v[118:121], v[168:171], v[202:205], v[118:121]
	v_mfma_f32_16x16x32_bf16 v[114:117], v[194:197], v[202:205], v[114:117]
	v_mfma_f32_16x16x32_bf16 v[102:105], v[168:171], v[210:213], v[102:105]
	v_mfma_f32_16x16x32_bf16 v[98:101], v[194:197], v[210:213], v[98:101]
	v_mfma_f32_16x16x32_bf16 v[86:89], v[168:171], v[218:221], v[86:89]
	v_mfma_f32_16x16x32_bf16 v[82:85], v[194:197], v[218:221], v[82:85]
	v_mfma_f32_16x16x32_bf16 v[70:73], v[168:171], v[230:233], v[70:73]
	v_mfma_f32_16x16x32_bf16 v[66:69], v[194:197], v[230:233], v[66:69]
	v_mfma_f32_16x16x32_bf16 v[118:121], v[190:193], v[206:209], v[118:121]
	v_mfma_f32_16x16x32_bf16 v[114:117], v[198:201], v[206:209], v[114:117]
	v_mfma_f32_16x16x32_bf16 v[102:105], v[190:193], v[214:217], v[102:105]
	v_mfma_f32_16x16x32_bf16 v[98:101], v[198:201], v[214:217], v[98:101]
	v_mfma_f32_16x16x32_bf16 v[86:89], v[190:193], v[226:229], v[86:89]
	v_mfma_f32_16x16x32_bf16 v[82:85], v[198:201], v[226:229], v[82:85]
	v_mfma_f32_16x16x32_bf16 v[70:73], v[190:193], v[234:237], v[70:73]
	v_mfma_f32_16x16x32_bf16 v[66:69], v[198:201], v[234:237], v[66:69]
	s_setprio 0
	s_barrier
	s_add_i32 s29, s94, s75
	v_lshl_add_u64 v[222:223], s[60:61], 0, v[148:149]
	s_mov_b32 m0, s29
	ds_read_b128 v[202:205], v184 offset:16384
	ds_read_b128 v[206:209], v184 offset:17408
	ds_read_b128 v[210:213], v184 offset:18432
	ds_read_b128 v[214:217], v184 offset:19456
	ds_read_b128 v[218:221], v184 offset:20480
	ds_read_b128 v[226:229], v184 offset:21504
	ds_read_b128 v[230:233], v184 offset:22528
	ds_read_b128 v[234:237], v184 offset:23552
	global_load_lds_dwordx4 v[222:223], off
	s_add_i32 m0, s29, 0x2000
	s_add_u32 s30, s60, 0x40000
	v_lshl_add_u64 v[224:225], s[60:61], 0, v[152:153]
	s_addc_u32 s31, s61, 0
	s_add_i32 s29, s95, s75
	global_load_lds_dwordx4 v[224:225], off
	v_lshl_add_u64 v[240:241], s[30:31], 0, v[148:149]
	s_mov_b32 m0, s29
	v_lshl_add_u64 v[242:243], s[62:63], 0, v[150:151]
	global_load_lds_dwordx4 v[240:241], off
	v_lshl_add_u64 v[240:241], s[30:31], 0, v[152:153]
	s_add_i32 m0, s29, 0x2000
	s_nop 0
	global_load_lds_dwordx4 v[240:241], off
	v_lshl_add_u64 v[240:241], s[62:63], 0, v[146:147]
	s_mov_b32 m0, s76
	s_nop 0
	global_load_lds_dwordx4 v[240:241], off
	s_mov_b32 m0, s77
	s_nop 0
	global_load_lds_dwordx4 v[242:243], off
	s_cmp_lg_u32 s98, 1
	s_cbranch_scc1 .Lp2w_s2_b
	s_waitcnt vmcnt(24)
	s_branch .Lp2w_s2_j

.Lp2w_s2_j:
	s_mov_b32 s98, 0
	s_waitcnt lgkmcnt(0)
	s_barrier
	s_setprio 1
	s_waitcnt lgkmcnt(0)
	v_mfma_f32_16x16x32_bf16 v[62:65], v[130:133], v[202:205], v[62:65]
	v_mfma_f32_16x16x32_bf16 v[58:61], v[138:141], v[202:205], v[58:61]
	v_mfma_f32_16x16x32_bf16 v[46:49], v[130:133], v[210:213], v[46:49]
	v_mfma_f32_16x16x32_bf16 v[42:45], v[138:141], v[210:213], v[42:45]
	v_mfma_f32_16x16x32_bf16 v[30:33], v[130:133], v[218:221], v[30:33]
	v_mfma_f32_16x16x32_bf16 v[26:29], v[138:141], v[218:221], v[26:29]
	v_mfma_f32_16x16x32_bf16 v[14:17], v[130:133], v[230:233], v[14:17]
	v_mfma_f32_16x16x32_bf16 v[10:13], v[138:141], v[230:233], v[10:13]
	v_mfma_f32_16x16x32_bf16 v[62:65], v[134:137], v[206:209], v[62:65]
	v_mfma_f32_16x16x32_bf16 v[58:61], v[142:145], v[206:209], v[58:61]
	v_mfma_f32_16x16x32_bf16 v[46:49], v[134:137], v[214:217], v[46:49]
	v_mfma_f32_16x16x32_bf16 v[42:45], v[142:145], v[214:217], v[42:45]
	v_mfma_f32_16x16x32_bf16 v[30:33], v[134:137], v[226:229], v[30:33]
	v_mfma_f32_16x16x32_bf16 v[26:29], v[142:145], v[226:229], v[26:29]
	v_mfma_f32_16x16x32_bf16 v[14:17], v[134:137], v[234:237], v[14:17]
	v_mfma_f32_16x16x32_bf16 v[10:13], v[142:145], v[234:237], v[10:13]
	s_setprio 0
	s_setprio 1
	v_mfma_f32_16x16x32_bf16 v[54:57], v[168:171], v[202:205], v[54:57]
	v_mfma_f32_16x16x32_bf16 v[50:53], v[194:197], v[202:205], v[50:53]
	v_mfma_f32_16x16x32_bf16 v[38:41], v[168:171], v[210:213], v[38:41]
	v_mfma_f32_16x16x32_bf16 v[34:37], v[194:197], v[210:213], v[34:37]
	v_mfma_f32_16x16x32_bf16 v[22:25], v[168:171], v[218:221], v[22:25]
	v_mfma_f32_16x16x32_bf16 v[18:21], v[194:197], v[218:221], v[18:21]
	v_mfma_f32_16x16x32_bf16 v[6:9], v[168:171], v[230:233], v[6:9]
	v_mfma_f32_16x16x32_bf16 v[2:5], v[194:197], v[230:233], v[2:5]
	v_mfma_f32_16x16x32_bf16 v[54:57], v[190:193], v[206:209], v[54:57]
	v_mfma_f32_16x16x32_bf16 v[50:53], v[198:201], v[206:209], v[50:53]
	v_mfma_f32_16x16x32_bf16 v[38:41], v[190:193], v[214:217], v[38:41]
	v_mfma_f32_16x16x32_bf16 v[34:37], v[198:201], v[214:217], v[34:37]
	v_mfma_f32_16x16x32_bf16 v[22:25], v[190:193], v[226:229], v[22:25]
	v_mfma_f32_16x16x32_bf16 v[18:21], v[198:201], v[226:229], v[18:21]
	v_mfma_f32_16x16x32_bf16 v[6:9], v[190:193], v[234:237], v[6:9]
	v_mfma_f32_16x16x32_bf16 v[2:5], v[198:201], v[234:237], v[2:5]
	s_setprio 0
	s_barrier
	s_add_i32 s29, 0, 0x18000
	s_add_i32 s33, 0, 0x1c000
	v_add_u32_e32 v142, s29, v157
	v_add_u32_e32 v154, s33, v157
	ds_read_b128 v[130:133], v142
	ds_read_b128 v[134:137], v142 offset:1024
	ds_read_b128 v[138:141], v142 offset:2048
	ds_read_b128 v[142:145], v142 offset:3072
	ds_read_b128 v[168:171], v154
	ds_read_b128 v[190:193], v154 offset:1024
	ds_read_b128 v[194:197], v154 offset:2048
	ds_read_b128 v[198:201], v154 offset:3072
	s_add_u32 s30, s62, 0x40000
	s_addc_u32 s31, s63, 0
	s_mov_b32 m0, s78
	v_lshl_add_u64 v[244:245], s[30:31], 0, v[146:147]
	ds_read_b128 v[202:205], v184 offset:32768
	ds_read_b128 v[206:209], v184 offset:33792
	ds_read_b128 v[210:213], v184 offset:34816
	ds_read_b128 v[214:217], v184 offset:35840
	ds_read_b128 v[218:221], v184 offset:36864
	ds_read_b128 v[226:229], v184 offset:37888
	ds_read_b128 v[230:233], v184 offset:38912
	ds_read_b128 v[234:237], v184 offset:39936
	global_load_lds_dwordx4 v[244:245], off
	v_lshl_add_u64 v[244:245], s[30:31], 0, v[150:151]
	s_mov_b32 m0, s79
	s_nop 0
	global_load_lds_dwordx4 v[244:245], off
	s_waitcnt vmcnt(8)
	s_waitcnt lgkmcnt(0)
	s_barrier
	s_setprio 1
	s_waitcnt lgkmcnt(0)
	v_mfma_f32_16x16x32_bf16 v[126:129], v[130:133], v[202:205], v[126:129]
	v_mfma_f32_16x16x32_bf16 v[122:125], v[138:141], v[202:205], v[122:125]
	v_mfma_f32_16x16x32_bf16 v[110:113], v[130:133], v[210:213], v[110:113]
	v_mfma_f32_16x16x32_bf16 v[106:109], v[138:141], v[210:213], v[106:109]
	v_mfma_f32_16x16x32_bf16 v[94:97], v[130:133], v[218:221], v[94:97]
	v_mfma_f32_16x16x32_bf16 v[90:93], v[138:141], v[218:221], v[90:93]
	v_mfma_f32_16x16x32_bf16 v[78:81], v[130:133], v[230:233], v[78:81]
	v_mfma_f32_16x16x32_bf16 v[74:77], v[138:141], v[230:233], v[74:77]
	v_mfma_f32_16x16x32_bf16 v[126:129], v[134:137], v[206:209], v[126:129]
	v_mfma_f32_16x16x32_bf16 v[122:125], v[142:145], v[206:209], v[122:125]
	v_mfma_f32_16x16x32_bf16 v[110:113], v[134:137], v[214:217], v[110:113]
	v_mfma_f32_16x16x32_bf16 v[106:109], v[142:145], v[214:217], v[106:109]
	v_mfma_f32_16x16x32_bf16 v[94:97], v[134:137], v[226:229], v[94:97]
	v_mfma_f32_16x16x32_bf16 v[90:93], v[142:145], v[226:229], v[90:93]
	v_mfma_f32_16x16x32_bf16 v[78:81], v[134:137], v[234:237], v[78:81]
	v_mfma_f32_16x16x32_bf16 v[74:77], v[142:145], v[234:237], v[74:77]
	s_setprio 0
	s_setprio 1
	v_mfma_f32_16x16x32_bf16 v[118:121], v[168:171], v[202:205], v[118:121]
	v_mfma_f32_16x16x32_bf16 v[114:117], v[194:197], v[202:205], v[114:117]
	v_mfma_f32_16x16x32_bf16 v[102:105], v[168:171], v[210:213], v[102:105]
	v_mfma_f32_16x16x32_bf16 v[98:101], v[194:197], v[210:213], v[98:101]
	v_mfma_f32_16x16x32_bf16 v[86:89], v[168:171], v[218:221], v[86:89]
	v_mfma_f32_16x16x32_bf16 v[82:85], v[194:197], v[218:221], v[82:85]
	v_mfma_f32_16x16x32_bf16 v[70:73], v[168:171], v[230:233], v[70:73]
	v_mfma_f32_16x16x32_bf16 v[66:69], v[194:197], v[230:233], v[66:69]
	v_mfma_f32_16x16x32_bf16 v[118:121], v[190:193], v[206:209], v[118:121]
	v_mfma_f32_16x16x32_bf16 v[114:117], v[198:201], v[206:209], v[114:117]
	v_mfma_f32_16x16x32_bf16 v[102:105], v[190:193], v[214:217], v[102:105]
	v_mfma_f32_16x16x32_bf16 v[98:101], v[198:201], v[214:217], v[98:101]
	v_mfma_f32_16x16x32_bf16 v[86:89], v[190:193], v[226:229], v[86:89]
	v_mfma_f32_16x16x32_bf16 v[82:85], v[198:201], v[226:229], v[82:85]
	v_mfma_f32_16x16x32_bf16 v[70:73], v[190:193], v[234:237], v[70:73]
	v_mfma_f32_16x16x32_bf16 v[66:69], v[198:201], v[234:237], v[66:69]
	s_setprio 0
	s_barrier
	s_add_i32 s29, s29, s75
	v_lshl_add_u64 v[222:223], v[222:223], 0, s[24:25]
	s_mov_b32 m0, s29
	ds_read_b128 v[202:205], v184 offset:49152
	ds_read_b128 v[206:209], v184 offset:50176
	ds_read_b128 v[210:213], v184 offset:51200
	ds_read_b128 v[214:217], v184 offset:52224
	ds_read_b128 v[218:221], v184 offset:53248
	ds_read_b128 v[226:229], v184 offset:54272
	ds_read_b128 v[230:233], v184 offset:55296
	ds_read_b128 v[234:237], v184 offset:56320
	global_load_lds_dwordx4 v[222:223], off
	s_add_i32 m0, s29, 0x2000
	s_add_u32 s30, s60, 0x40080
	v_lshl_add_u64 v[222:223], v[224:225], 0, s[24:25]
	s_addc_u32 s31, s61, 0
	s_add_i32 s29, s33, s75
	global_load_lds_dwordx4 v[222:223], off
	v_lshl_add_u64 v[222:223], s[30:31], 0, v[148:149]
	s_mov_b32 m0, s29
	s_nop 0
	global_load_lds_dwordx4 v[222:223], off
	v_lshl_add_u64 v[222:223], s[30:31], 0, v[152:153]
	s_add_i32 m0, s29, 0x2000
	s_nop 0
	global_load_lds_dwordx4 v[222:223], off
	v_lshl_add_u64 v[222:223], v[240:241], 0, s[24:25]
	s_mov_b32 m0, s86
	s_nop 0
	global_load_lds_dwordx4 v[222:223], off
	v_lshl_add_u64 v[222:223], v[242:243], 0, s[24:25]
	s_mov_b32 m0, s87
	s_nop 0
	global_load_lds_dwordx4 v[222:223], off
	s_waitcnt vmcnt(8)
	s_waitcnt lgkmcnt(0)
	s_barrier
	s_setprio 1
	s_waitcnt lgkmcnt(0)
	v_mfma_f32_16x16x32_bf16 v[62:65], v[130:133], v[202:205], v[62:65]
	v_mfma_f32_16x16x32_bf16 v[58:61], v[138:141], v[202:205], v[58:61]
	v_mfma_f32_16x16x32_bf16 v[46:49], v[130:133], v[210:213], v[46:49]
	v_mfma_f32_16x16x32_bf16 v[42:45], v[138:141], v[210:213], v[42:45]
	v_mfma_f32_16x16x32_bf16 v[30:33], v[130:133], v[218:221], v[30:33]
	v_mfma_f32_16x16x32_bf16 v[26:29], v[138:141], v[218:221], v[26:29]
	v_mfma_f32_16x16x32_bf16 v[14:17], v[130:133], v[230:233], v[14:17]
	v_mfma_f32_16x16x32_bf16 v[10:13], v[138:141], v[230:233], v[10:13]
	v_mfma_f32_16x16x32_bf16 v[62:65], v[134:137], v[206:209], v[62:65]
	v_mfma_f32_16x16x32_bf16 v[58:61], v[142:145], v[206:209], v[58:61]
	v_mfma_f32_16x16x32_bf16 v[46:49], v[134:137], v[214:217], v[46:49]
	v_mfma_f32_16x16x32_bf16 v[42:45], v[142:145], v[214:217], v[42:45]
	v_mfma_f32_16x16x32_bf16 v[30:33], v[134:137], v[226:229], v[30:33]
	v_mfma_f32_16x16x32_bf16 v[26:29], v[142:145], v[226:229], v[26:29]
	v_mfma_f32_16x16x32_bf16 v[14:17], v[134:137], v[234:237], v[14:17]
	v_mfma_f32_16x16x32_bf16 v[10:13], v[142:145], v[234:237], v[10:13]
	s_setprio 0
	s_setprio 1
	v_mfma_f32_16x16x32_bf16 v[54:57], v[168:171], v[202:205], v[54:57]
	v_mfma_f32_16x16x32_bf16 v[50:53], v[194:197], v[202:205], v[50:53]
	v_mfma_f32_16x16x32_bf16 v[38:41], v[168:171], v[210:213], v[38:41]
	v_mfma_f32_16x16x32_bf16 v[34:37], v[194:197], v[210:213], v[34:37]
	v_mfma_f32_16x16x32_bf16 v[22:25], v[168:171], v[218:221], v[22:25]
	v_mfma_f32_16x16x32_bf16 v[18:21], v[194:197], v[218:221], v[18:21]
	v_mfma_f32_16x16x32_bf16 v[6:9], v[168:171], v[230:233], v[6:9]
	v_mfma_f32_16x16x32_bf16 v[2:5], v[194:197], v[230:233], v[2:5]
	v_mfma_f32_16x16x32_bf16 v[54:57], v[190:193], v[206:209], v[54:57]
	v_mfma_f32_16x16x32_bf16 v[50:53], v[198:201], v[206:209], v[50:53]
	v_mfma_f32_16x16x32_bf16 v[38:41], v[190:193], v[214:217], v[38:41]
	v_mfma_f32_16x16x32_bf16 v[34:37], v[198:201], v[214:217], v[34:37]
	v_mfma_f32_16x16x32_bf16 v[22:25], v[190:193], v[226:229], v[22:25]
	v_mfma_f32_16x16x32_bf16 v[18:21], v[198:201], v[226:229], v[18:21]
	v_mfma_f32_16x16x32_bf16 v[6:9], v[190:193], v[234:237], v[6:9]
	v_mfma_f32_16x16x32_bf16 v[2:5], v[198:201], v[234:237], v[2:5]
	s_setprio 0
	s_barrier
	s_add_i32 s28, s28, 2
	s_add_u32 s58, s58, 0x100
	s_addc_u32 s59, s59, 0
	s_add_u32 s7, s7, 0x100
	s_addc_u32 s14, s14, 0
	s_cmp_gt_u32 s28, 13
	s_cbranch_scc0 .LBB0_257
	s_and_b64 vcc, exec, s[26:27]
	s_cbranch_vccz .LBB0_260
	s_barrier
.LBB0_260:
	s_cmp_eq_u32 s6, 11
	s_cselect_b32 s98, 2, 1
	s_lshl_b32 s1, s4, 8
	s_add_i32 s1, s1, s85
	s_cmp_lt_i32 s6, 3
	v_or_b32_e32 v168, s1, v1
	s_cbranch_scc0 .LBB0_266
	s_cmp_eq_u32 s6, 2
	s_cselect_b64 s[4:5], -1, 0
	s_and_b64 s[28:29], s[4:5], s[36:37]
	s_andn2_b64 vcc, exec, s[28:29]
	s_mov_b64 s[58:59], -1
	s_cbranch_vccz .LBB0_263
	s_and_b64 s[28:29], s[4:5], exec
	s_cselect_b32 s29, s11, s9
	s_cselect_b32 s28, s10, s8
	global_load_dwordx4 v[138:141], v185, s[28:29]
	global_load_dwordx4 v[134:137], v185, s[28:29] offset:64
	global_load_dwordx4 v[130:133], v185, s[28:29] offset:128
	v_and_b32_e32 v143, 64, v189
	v_xor_b32_e32 v142, 16, v189
	v_add_u32_e32 v165, 64, v143
	v_cmp_lt_i32_e32 vcc, v142, v165
	v_pk_mul_f32 v[144:145], v[126:127], v[126:127]
	v_mul_f32_e32 v169, v114, v114
	v_cndmask_b32_e32 v142, v189, v142, vcc
	v_lshlrev_b32_e32 v190, 2, v142
	v_pk_mul_f32 v[142:143], v[128:129], v[128:129]
	v_mul_f32_e32 v191, v117, v117
	v_pk_mov_b32 v[170:171], v[144:145], v[142:143] op_sel:[1,0]
	v_mov_b32_e32 v145, v143
	v_pk_add_f32 v[142:143], v[170:171], v[144:145]
	v_pk_mul_f32 v[144:145], v[124:125], v[124:125]
	v_pk_mul_f32 v[170:171], v[122:123], v[122:123]
	v_pk_add_f32 v[142:143], v[142:143], v[142:143] op_sel:[0,1] op_sel_hi:[1,0]
	v_pk_mov_b32 v[192:193], v[170:171], v[144:145] op_sel:[1,0]
	v_mov_b32_e32 v171, v145
	v_pk_add_f32 v[144:145], v[192:193], v[170:171]
	v_mul_f32_e32 v170, v115, v115
	v_pk_add_f32 v[144:145], v[144:145], v[144:145] op_sel:[0,1] op_sel_hi:[1,0]
	v_mov_b32_e32 v143, v169
	v_mov_b32_e32 v145, v170
	v_pk_add_f32 v[142:143], v[142:143], v[144:145]
	v_mul_f32_e32 v144, v119, v119
	v_mul_f32_e32 v171, v116, v116
	v_pk_fma_f32 v[144:145], v[118:119], v[118:119], v[144:145] op_sel_hi:[1,1,0]
	v_mul_f32_e32 v170, v121, v121
	v_mov_b32_e32 v145, v171
	v_pk_fma_f32 v[170:171], v[120:121], v[120:121], v[170:171] op_sel_hi:[1,1,0]
	s_lshl_b32 s0, s6, 8
	v_mov_b32_e32 v171, v191
	v_pk_add_f32 v[144:145], v[144:145], v[170:171]
	s_or_b32 s30, s0, s88
	v_pk_add_f32 v[142:143], v[142:143], v[144:145]
	v_xor_b32_e32 v144, 32, v189
	v_add_f32_e32 v142, v142, v143
	ds_bpermute_b32 v143, v190, v142
	v_cmp_lt_i32_e32 vcc, v144, v165
	s_ashr_i32 s31, s30, 31
	v_cndmask_b32_e64 v154, v188, 1.0, s[4:5]
	v_cndmask_b32_e32 v144, v189, v144, vcc
	v_lshlrev_b32_e32 v191, 2, v144
	s_waitcnt lgkmcnt(0)
	v_add_f32_e32 v165, v142, v143
	global_load_dwordx4 v[142:145], v185, s[28:29] offset:192
	ds_bpermute_b32 v169, v191, v165
	s_lshl_b64 s[28:29], s[30:31], 1
	s_add_u32 s0, s80, s28
	s_addc_u32 s2, s81, s29
	s_and_b64 s[4:5], s[4:5], exec
	s_waitcnt lgkmcnt(0)
	v_add_f32_e32 v165, v165, v169
	v_fmamk_f32 v165, v165, 0x3c800000, v186
	v_mul_f32_e32 v169, 0x4f800000, v165
	v_cmp_gt_f32_e32 vcc, s96, v165
	s_cselect_b32 s29, s92, s2
	s_cselect_b32 s28, s91, s0
	v_cndmask_b32_e32 v165, v165, v169, vcc
	v_sqrt_f32_e32 v169, v165
	s_cselect_b32 s0, 7, 9
	s_and_b32 s1, s1, 0x7c0
	s_mov_b64 s[58:59], 0
	v_add_u32_e32 v170, -1, v169
	v_fma_f32 v171, -v170, v169, v165
	v_cmp_ge_f32_e64 s[4:5], 0, v171
	v_add_u32_e32 v171, 1, v169
	s_nop 0
	v_cndmask_b32_e64 v170, v169, v170, s[4:5]
	v_fma_f32 v169, -v171, v169, v165
	v_cmp_lt_f32_e64 s[4:5], 0, v169
	s_nop 1
	v_cndmask_b32_e64 v169, v170, v171, s[4:5]
	v_mul_f32_e32 v170, 0x37800000, v169
	v_cndmask_b32_e32 v169, v169, v170, vcc
	v_cmp_class_f32_e32 vcc, v165, v187
	s_nop 1
	v_cndmask_b32_e32 v169, v169, v165, vcc
	v_div_scale_f32 v192, s[4:5], v169, v169, v154
	v_rcp_f32_e32 v193, v192
	v_mov_b32_e32 v165, v155
	v_lshl_add_u64 v[170:171], s[28:29], 0, v[164:165]
	v_fma_f32 v165, -v192, v193, 1.0
	v_fmac_f32_e32 v193, v165, v193
	v_div_scale_f32 v165, vcc, v154, v169, v154
	v_mul_f32_e32 v194, v165, v193
	v_fma_f32 v195, -v192, v194, v165
	v_fmac_f32_e32 v194, v195, v193
	v_fma_f32 v165, -v192, v194, v165
	v_div_fmas_f32 v165, v165, v193, v194
	v_div_fixup_f32 v200, v165, v169, v154
	v_ashrrev_i32_e32 v169, 31, v168
	v_lshlrev_b64 v[192:193], s0, v[168:169]
	v_add_u32_e32 v165, s1, v172
	v_lshl_add_u64 v[202:203], v[192:193], 1, v[170:171]
	v_add_u32_e32 v169, s1, v173
	ds_read_b128 v[192:195], v165
	ds_read_b128 v[196:199], v169
	v_pk_mul_f32 v[208:209], v[122:123], v[200:201] op_sel_hi:[1,0]
	v_pk_mul_f32 v[210:211], v[124:125], v[200:201] op_sel_hi:[1,0]
	v_pk_mul_f32 v[204:205], v[128:129], v[200:201] op_sel_hi:[1,0]
	v_pk_mul_f32 v[206:207], v[126:127], v[200:201] op_sel_hi:[1,0]
	s_waitcnt vmcnt(0)
	v_pk_mul_f32 v[210:211], v[136:137], v[210:211]
	v_pk_mul_f32 v[208:209], v[134:135], v[208:209]
	v_pk_mul_f32 v[206:207], v[138:139], v[206:207]
	v_pk_mul_f32 v[204:205], v[140:141], v[204:205]
	s_waitcnt lgkmcnt(0)
	v_pk_mul_f32 v[212:213], v[196:197], v[208:209]
	v_pk_mul_f32 v[214:215], v[198:199], v[210:211]
	v_pk_fma_f32 v[212:213], v[192:193], v[206:207], v[212:213] neg_lo:[0,0,1] neg_hi:[0,0,1]
	v_pk_fma_f32 v[214:215], v[194:195], v[204:205], v[214:215] neg_lo:[0,0,1] neg_hi:[0,0,1]
	v_pk_mul_f32 v[192:193], v[192:193], v[208:209]
	v_pk_mul_f32 v[194:195], v[194:195], v[210:211]
	v_pk_mul_f32 v[210:211], v[112:113], v[112:113]
	v_pk_fma_f32 v[198:199], v[198:199], v[204:205], v[194:195]
	v_pk_fma_f32 v[194:195], v[196:197], v[206:207], v[192:193]
	v_cvt_pk_bf16_f32 v192, v212, v213
	v_pk_mul_f32 v[212:213], v[110:111], v[110:111]
	v_cvt_pk_bf16_f32 v193, v214, v215
	v_cvt_pk_bf16_f32 v194, v194, v195
	v_cvt_pk_bf16_f32 v195, v198, v199
	global_store_dwordx4 v[202:203], v[192:195], off
	v_pk_mov_b32 v[214:215], v[212:213], v[210:211] op_sel:[1,0]
	v_mov_b32_e32 v213, v211
	v_pk_add_f32 v[210:211], v[214:215], v[212:213]
	v_pk_mul_f32 v[212:213], v[108:109], v[108:109]
	v_pk_mul_f32 v[214:215], v[106:107], v[106:107]
	v_pk_add_f32 v[210:211], v[210:211], v[210:211] op_sel:[0,1] op_sel_hi:[1,0]
	v_pk_mov_b32 v[216:217], v[214:215], v[212:213] op_sel:[1,0]
	v_mov_b32_e32 v215, v213
	v_pk_add_f32 v[212:213], v[216:217], v[214:215]
	v_mul_f32_e32 v214, v98, v98
	v_mul_f32_e32 v215, v99, v99
	v_pk_add_f32 v[212:213], v[212:213], v[212:213] op_sel:[0,1] op_sel_hi:[1,0]
	v_mov_b32_e32 v211, v214
	v_mov_b32_e32 v213, v215
	v_pk_add_f32 v[210:211], v[210:211], v[212:213]
	v_mul_f32_e32 v212, v103, v103
	v_mul_f32_e32 v214, v105, v105
	v_mul_f32_e32 v216, v100, v100
	v_mul_f32_e32 v217, v101, v101
	v_pk_fma_f32 v[212:213], v[102:103], v[102:103], v[212:213] op_sel_hi:[1,1,0]
	v_pk_fma_f32 v[214:215], v[104:105], v[104:105], v[214:215] op_sel_hi:[1,1,0]
	v_mov_b32_e32 v213, v216
	v_mov_b32_e32 v215, v217
	v_pk_add_f32 v[212:213], v[212:213], v[214:215]
	ds_read_b128 v[192:195], v174
	ds_read_b128 v[196:199], v175
	v_pk_add_f32 v[210:211], v[210:211], v[212:213]
	v_pk_mul_f32 v[204:205], v[120:121], v[200:201] op_sel_hi:[1,0]
	v_add_f32_e32 v214, v210, v211
	ds_bpermute_b32 v215, v190, v214
	v_pk_mul_f32 v[206:207], v[118:119], v[200:201] op_sel_hi:[1,0]
	v_pk_mul_f32 v[208:209], v[114:115], v[200:201] op_sel_hi:[1,0]
	v_pk_mul_f32 v[200:201], v[116:117], v[200:201] op_sel_hi:[1,0]
	v_pk_mul_f32 v[208:209], v[142:143], v[208:209]
	s_waitcnt lgkmcnt(0)
	v_add_f32_e32 v214, v214, v215
	ds_bpermute_b32 v215, v191, v214
	v_pk_mul_f32 v[200:201], v[144:145], v[200:201]
	v_pk_mul_f32 v[206:207], v[130:131], v[206:207]
	v_pk_mul_f32 v[204:205], v[132:133], v[204:205]
	v_pk_mul_f32 v[210:211], v[196:197], v[208:209]
	v_pk_mul_f32 v[212:213], v[198:199], v[200:201]
	v_pk_fma_f32 v[210:211], v[192:193], v[206:207], v[210:211] neg_lo:[0,0,1] neg_hi:[0,0,1]
	v_pk_fma_f32 v[212:213], v[194:195], v[204:205], v[212:213] neg_lo:[0,0,1] neg_hi:[0,0,1]
	v_pk_mul_f32 v[192:193], v[192:193], v[208:209]
	v_pk_mul_f32 v[194:195], v[194:195], v[200:201]
	s_nop 0
	v_pk_fma_f32 v[198:199], v[198:199], v[204:205], v[194:195]
	v_pk_fma_f32 v[194:195], v[196:197], v[206:207], v[192:193]
	s_waitcnt lgkmcnt(0)
	v_add_f32_e32 v192, v214, v215
	v_fmamk_f32 v192, v192, 0x3c800000, v186
	v_mul_f32_e32 v193, 0x4f800000, v192
	v_cmp_gt_f32_e32 vcc, s96, v192
	s_nop 1
	v_cndmask_b32_e32 v196, v192, v193, vcc
	v_sqrt_f32_e32 v197, v196
	v_cvt_pk_bf16_f32 v192, v210, v211
	v_cvt_pk_bf16_f32 v193, v212, v213
	v_cvt_pk_bf16_f32 v194, v194, v195
	s_nop 0
	v_add_u32_e32 v195, -1, v197
	v_fma_f32 v200, -v195, v197, v196
	v_cmp_ge_f32_e64 s[4:5], 0, v200
	v_add_u32_e32 v200, 1, v197
	s_nop 0
	v_cndmask_b32_e64 v195, v197, v195, s[4:5]
	v_fma_f32 v197, -v200, v197, v196
	v_cmp_lt_f32_e64 s[4:5], 0, v197
	s_nop 1
	v_cndmask_b32_e64 v195, v195, v200, s[4:5]
	v_mul_f32_e32 v197, 0x37800000, v195
	v_cndmask_b32_e32 v195, v195, v197, vcc
	v_cmp_class_f32_e32 vcc, v196, v187
	s_nop 1
	v_cndmask_b32_e32 v196, v195, v196, vcc
	v_div_scale_f32 v197, s[4:5], v196, v196, v154
	v_rcp_f32_e32 v200, v197
	v_cvt_pk_bf16_f32 v195, v198, v199
	global_store_dwordx4 v[202:203], v[192:195], off offset:64
	s_nop 1
	v_fma_f32 v193, -v197, v200, 1.0
	v_fmac_f32_e32 v200, v193, v200
	v_div_scale_f32 v193, vcc, v154, v196, v154
	v_mul_f32_e32 v194, v193, v200
	v_fma_f32 v195, -v197, v194, v193
	v_fmac_f32_e32 v194, v195, v200
	v_fma_f32 v193, -v197, v194, v193
	v_or_b32_e32 v192, 16, v168
	v_div_fmas_f32 v193, v193, v200, v194
	v_div_fixup_f32 v200, v193, v196, v154
	v_ashrrev_i32_e32 v193, 31, v192
	v_lshlrev_b64 v[192:193], s0, v[192:193]
	v_lshl_add_u64 v[202:203], v[192:193], 1, v[170:171]
	ds_read_b128 v[192:195], v165
	ds_read_b128 v[196:199], v169
	v_pk_mul_f32 v[208:209], v[106:107], v[200:201] op_sel_hi:[1,0]
	v_pk_mul_f32 v[210:211], v[108:109], v[200:201] op_sel_hi:[1,0]
	v_pk_mul_f32 v[204:205], v[112:113], v[200:201] op_sel_hi:[1,0]
	v_pk_mul_f32 v[206:207], v[110:111], v[200:201] op_sel_hi:[1,0]
	v_pk_mul_f32 v[210:211], v[136:137], v[210:211]
	v_pk_mul_f32 v[208:209], v[134:135], v[208:209]
	v_pk_mul_f32 v[206:207], v[138:139], v[206:207]
	v_pk_mul_f32 v[204:205], v[140:141], v[204:205]
	s_waitcnt lgkmcnt(0)
	v_pk_mul_f32 v[212:213], v[196:197], v[208:209]
	v_pk_mul_f32 v[214:215], v[198:199], v[210:211]
	v_pk_fma_f32 v[212:213], v[192:193], v[206:207], v[212:213] neg_lo:[0,0,1] neg_hi:[0,0,1]
	v_pk_fma_f32 v[214:215], v[194:195], v[204:205], v[214:215] neg_lo:[0,0,1] neg_hi:[0,0,1]
	v_pk_mul_f32 v[192:193], v[192:193], v[208:209]
	v_pk_mul_f32 v[194:195], v[194:195], v[210:211]
	v_pk_mul_f32 v[210:211], v[96:97], v[96:97]
	v_pk_fma_f32 v[198:199], v[198:199], v[204:205], v[194:195]
	v_pk_fma_f32 v[194:195], v[196:197], v[206:207], v[192:193]
	v_cvt_pk_bf16_f32 v192, v212, v213
	v_pk_mul_f32 v[212:213], v[94:95], v[94:95]
	v_cvt_pk_bf16_f32 v193, v214, v215
	v_cvt_pk_bf16_f32 v194, v194, v195
	v_cvt_pk_bf16_f32 v195, v198, v199
	global_store_dwordx4 v[202:203], v[192:195], off
	v_pk_mov_b32 v[214:215], v[212:213], v[210:211] op_sel:[1,0]
	v_mov_b32_e32 v213, v211
	v_pk_add_f32 v[210:211], v[214:215], v[212:213]
	v_pk_mul_f32 v[212:213], v[92:93], v[92:93]
	v_pk_mul_f32 v[214:215], v[90:91], v[90:91]
	v_pk_add_f32 v[210:211], v[210:211], v[210:211] op_sel:[0,1] op_sel_hi:[1,0]
	v_pk_mov_b32 v[216:217], v[214:215], v[212:213] op_sel:[1,0]
	v_mov_b32_e32 v215, v213
	v_pk_add_f32 v[212:213], v[216:217], v[214:215]
	v_mul_f32_e32 v214, v82, v82
	v_mul_f32_e32 v215, v83, v83
	v_pk_add_f32 v[212:213], v[212:213], v[212:213] op_sel:[0,1] op_sel_hi:[1,0]
	v_mov_b32_e32 v211, v214
	v_mov_b32_e32 v213, v215
	v_pk_add_f32 v[210:211], v[210:211], v[212:213]
	v_mul_f32_e32 v212, v87, v87
	v_mul_f32_e32 v214, v89, v89
	v_mul_f32_e32 v216, v84, v84
	v_mul_f32_e32 v217, v85, v85
	v_pk_fma_f32 v[212:213], v[86:87], v[86:87], v[212:213] op_sel_hi:[1,1,0]
	v_pk_fma_f32 v[214:215], v[88:89], v[88:89], v[214:215] op_sel_hi:[1,1,0]
	v_mov_b32_e32 v213, v216
	v_mov_b32_e32 v215, v217
	v_pk_add_f32 v[212:213], v[212:213], v[214:215]
	ds_read_b128 v[192:195], v176
	ds_read_b128 v[196:199], v177
	v_pk_add_f32 v[210:211], v[210:211], v[212:213]
	v_pk_mul_f32 v[204:205], v[104:105], v[200:201] op_sel_hi:[1,0]
	v_add_f32_e32 v214, v210, v211
	ds_bpermute_b32 v215, v190, v214
	v_pk_mul_f32 v[206:207], v[102:103], v[200:201] op_sel_hi:[1,0]
	v_pk_mul_f32 v[208:209], v[98:99], v[200:201] op_sel_hi:[1,0]
	v_pk_mul_f32 v[200:201], v[100:101], v[200:201] op_sel_hi:[1,0]
	v_pk_mul_f32 v[208:209], v[142:143], v[208:209]
	s_waitcnt lgkmcnt(0)
	v_add_f32_e32 v214, v214, v215
	ds_bpermute_b32 v215, v191, v214
	v_pk_mul_f32 v[200:201], v[144:145], v[200:201]
	v_pk_mul_f32 v[206:207], v[130:131], v[206:207]
	v_pk_mul_f32 v[204:205], v[132:133], v[204:205]
	v_pk_mul_f32 v[210:211], v[196:197], v[208:209]
	v_pk_mul_f32 v[212:213], v[198:199], v[200:201]
	v_pk_fma_f32 v[210:211], v[192:193], v[206:207], v[210:211] neg_lo:[0,0,1] neg_hi:[0,0,1]
	v_pk_fma_f32 v[212:213], v[194:195], v[204:205], v[212:213] neg_lo:[0,0,1] neg_hi:[0,0,1]
	v_pk_mul_f32 v[192:193], v[192:193], v[208:209]
	v_pk_mul_f32 v[194:195], v[194:195], v[200:201]
	s_nop 0
	v_pk_fma_f32 v[198:199], v[198:199], v[204:205], v[194:195]
	v_pk_fma_f32 v[194:195], v[196:197], v[206:207], v[192:193]
	s_waitcnt lgkmcnt(0)
	v_add_f32_e32 v192, v214, v215
	v_fmamk_f32 v192, v192, 0x3c800000, v186
	v_mul_f32_e32 v193, 0x4f800000, v192
	v_cmp_gt_f32_e32 vcc, s96, v192
	s_nop 1
	v_cndmask_b32_e32 v196, v192, v193, vcc
	v_sqrt_f32_e32 v197, v196
	v_cvt_pk_bf16_f32 v192, v210, v211
	v_cvt_pk_bf16_f32 v193, v212, v213
	v_cvt_pk_bf16_f32 v194, v194, v195
	s_nop 0
	v_add_u32_e32 v195, -1, v197
	v_fma_f32 v200, -v195, v197, v196
	v_cmp_ge_f32_e64 s[4:5], 0, v200
	v_add_u32_e32 v200, 1, v197
	s_nop 0
	v_cndmask_b32_e64 v195, v197, v195, s[4:5]
	v_fma_f32 v197, -v200, v197, v196
	v_cmp_lt_f32_e64 s[4:5], 0, v197
	s_nop 1
	v_cndmask_b32_e64 v195, v195, v200, s[4:5]
	v_mul_f32_e32 v197, 0x37800000, v195
	v_cndmask_b32_e32 v195, v195, v197, vcc
	v_cmp_class_f32_e32 vcc, v196, v187
	s_nop 1
	v_cndmask_b32_e32 v196, v195, v196, vcc
	v_div_scale_f32 v197, s[4:5], v196, v196, v154
	v_rcp_f32_e32 v200, v197
	v_cvt_pk_bf16_f32 v195, v198, v199
	global_store_dwordx4 v[202:203], v[192:195], off offset:64
	s_nop 1
	v_fma_f32 v193, -v197, v200, 1.0
	v_fmac_f32_e32 v200, v193, v200
	v_div_scale_f32 v193, vcc, v154, v196, v154
	v_mul_f32_e32 v194, v193, v200
	v_fma_f32 v195, -v197, v194, v193
	v_fmac_f32_e32 v194, v195, v200
	v_fma_f32 v193, -v197, v194, v193
	v_or_b32_e32 v192, 32, v168
	v_div_fmas_f32 v193, v193, v200, v194
	v_div_fixup_f32 v200, v193, v196, v154
	v_ashrrev_i32_e32 v193, 31, v192
	v_lshlrev_b64 v[192:193], s0, v[192:193]
	v_lshl_add_u64 v[202:203], v[192:193], 1, v[170:171]
	ds_read_b128 v[192:195], v165
	ds_read_b128 v[196:199], v169
	v_pk_mul_f32 v[208:209], v[90:91], v[200:201] op_sel_hi:[1,0]
	v_pk_mul_f32 v[210:211], v[92:93], v[200:201] op_sel_hi:[1,0]
	v_pk_mul_f32 v[204:205], v[96:97], v[200:201] op_sel_hi:[1,0]
	v_pk_mul_f32 v[206:207], v[94:95], v[200:201] op_sel_hi:[1,0]
	v_pk_mul_f32 v[210:211], v[136:137], v[210:211]
	v_pk_mul_f32 v[208:209], v[134:135], v[208:209]
	v_pk_mul_f32 v[206:207], v[138:139], v[206:207]
	v_pk_mul_f32 v[204:205], v[140:141], v[204:205]
	s_waitcnt lgkmcnt(0)
	v_pk_mul_f32 v[212:213], v[196:197], v[208:209]
	v_pk_mul_f32 v[214:215], v[198:199], v[210:211]
	v_pk_fma_f32 v[212:213], v[192:193], v[206:207], v[212:213] neg_lo:[0,0,1] neg_hi:[0,0,1]
	v_pk_fma_f32 v[214:215], v[194:195], v[204:205], v[214:215] neg_lo:[0,0,1] neg_hi:[0,0,1]
	v_pk_mul_f32 v[192:193], v[192:193], v[208:209]
	v_pk_mul_f32 v[194:195], v[194:195], v[210:211]
	v_pk_mul_f32 v[210:211], v[80:81], v[80:81]
	v_pk_fma_f32 v[198:199], v[198:199], v[204:205], v[194:195]
	v_pk_fma_f32 v[194:195], v[196:197], v[206:207], v[192:193]
	v_cvt_pk_bf16_f32 v192, v212, v213
	v_pk_mul_f32 v[212:213], v[78:79], v[78:79]
	v_cvt_pk_bf16_f32 v193, v214, v215
	v_cvt_pk_bf16_f32 v194, v194, v195
	v_cvt_pk_bf16_f32 v195, v198, v199
	global_store_dwordx4 v[202:203], v[192:195], off
	v_pk_mov_b32 v[214:215], v[212:213], v[210:211] op_sel:[1,0]
	v_mov_b32_e32 v213, v211
	v_pk_add_f32 v[210:211], v[214:215], v[212:213]
	v_pk_mul_f32 v[212:213], v[76:77], v[76:77]
	v_pk_mul_f32 v[214:215], v[74:75], v[74:75]
	v_pk_add_f32 v[210:211], v[210:211], v[210:211] op_sel:[0,1] op_sel_hi:[1,0]
	v_pk_mov_b32 v[216:217], v[214:215], v[212:213] op_sel:[1,0]
	v_mov_b32_e32 v215, v213
	v_pk_add_f32 v[212:213], v[216:217], v[214:215]
	v_mul_f32_e32 v214, v66, v66
	v_mul_f32_e32 v215, v67, v67
	v_pk_add_f32 v[212:213], v[212:213], v[212:213] op_sel:[0,1] op_sel_hi:[1,0]
	v_mov_b32_e32 v211, v214
	v_mov_b32_e32 v213, v215
	v_pk_add_f32 v[210:211], v[210:211], v[212:213]
	v_mul_f32_e32 v212, v71, v71
	v_mul_f32_e32 v214, v73, v73
	v_mul_f32_e32 v216, v68, v68
	v_mul_f32_e32 v217, v69, v69
	v_pk_fma_f32 v[212:213], v[70:71], v[70:71], v[212:213] op_sel_hi:[1,1,0]
	v_pk_fma_f32 v[214:215], v[72:73], v[72:73], v[214:215] op_sel_hi:[1,1,0]
	v_mov_b32_e32 v213, v216
	v_mov_b32_e32 v215, v217
	v_pk_add_f32 v[212:213], v[212:213], v[214:215]
	ds_read_b128 v[192:195], v178
	ds_read_b128 v[196:199], v179
	v_pk_add_f32 v[210:211], v[210:211], v[212:213]
	v_pk_mul_f32 v[204:205], v[88:89], v[200:201] op_sel_hi:[1,0]
	v_add_f32_e32 v214, v210, v211
	ds_bpermute_b32 v215, v190, v214
	v_pk_mul_f32 v[206:207], v[86:87], v[200:201] op_sel_hi:[1,0]
	v_pk_mul_f32 v[208:209], v[82:83], v[200:201] op_sel_hi:[1,0]
	v_pk_mul_f32 v[200:201], v[84:85], v[200:201] op_sel_hi:[1,0]
	v_pk_mul_f32 v[208:209], v[142:143], v[208:209]
	s_waitcnt lgkmcnt(0)
	v_add_f32_e32 v214, v214, v215
	ds_bpermute_b32 v215, v191, v214
	v_pk_mul_f32 v[200:201], v[144:145], v[200:201]
	v_pk_mul_f32 v[206:207], v[130:131], v[206:207]
	v_pk_mul_f32 v[204:205], v[132:133], v[204:205]
	v_pk_mul_f32 v[210:211], v[196:197], v[208:209]
	v_pk_mul_f32 v[212:213], v[198:199], v[200:201]
	v_pk_fma_f32 v[210:211], v[192:193], v[206:207], v[210:211] neg_lo:[0,0,1] neg_hi:[0,0,1]
	v_pk_fma_f32 v[212:213], v[194:195], v[204:205], v[212:213] neg_lo:[0,0,1] neg_hi:[0,0,1]
	v_pk_mul_f32 v[192:193], v[192:193], v[208:209]
	v_pk_mul_f32 v[194:195], v[194:195], v[200:201]
	s_nop 0
	v_pk_fma_f32 v[198:199], v[198:199], v[204:205], v[194:195]
	v_pk_fma_f32 v[194:195], v[196:197], v[206:207], v[192:193]
	s_waitcnt lgkmcnt(0)
	v_add_f32_e32 v192, v214, v215
	v_fmamk_f32 v192, v192, 0x3c800000, v186
	v_mul_f32_e32 v193, 0x4f800000, v192
	v_cmp_gt_f32_e32 vcc, s96, v192
	s_nop 1
	v_cndmask_b32_e32 v196, v192, v193, vcc
	v_sqrt_f32_e32 v197, v196
	v_cvt_pk_bf16_f32 v192, v210, v211
	v_cvt_pk_bf16_f32 v193, v212, v213
	v_cvt_pk_bf16_f32 v194, v194, v195
	s_nop 0
	v_add_u32_e32 v195, -1, v197
	v_fma_f32 v200, -v195, v197, v196
	v_cmp_ge_f32_e64 s[4:5], 0, v200
	v_add_u32_e32 v200, 1, v197
	s_nop 0
	v_cndmask_b32_e64 v195, v197, v195, s[4:5]
	v_fma_f32 v197, -v200, v197, v196
	v_cmp_lt_f32_e64 s[4:5], 0, v197
	s_nop 1
	v_cndmask_b32_e64 v195, v195, v200, s[4:5]
	v_mul_f32_e32 v197, 0x37800000, v195
	v_cndmask_b32_e32 v195, v195, v197, vcc
	v_cmp_class_f32_e32 vcc, v196, v187
	s_nop 1
	v_cndmask_b32_e32 v196, v195, v196, vcc
	v_div_scale_f32 v197, s[4:5], v196, v196, v154
	v_rcp_f32_e32 v200, v197
	v_cvt_pk_bf16_f32 v195, v198, v199
	global_store_dwordx4 v[202:203], v[192:195], off offset:64
	s_nop 1
	v_fma_f32 v193, -v197, v200, 1.0
	v_fmac_f32_e32 v200, v193, v200
	v_div_scale_f32 v193, vcc, v154, v196, v154
	v_mul_f32_e32 v194, v193, v200
	v_fma_f32 v195, -v197, v194, v193
	v_fmac_f32_e32 v194, v195, v200
	v_fma_f32 v193, -v197, v194, v193
	v_or_b32_e32 v192, 48, v168
	v_div_fmas_f32 v193, v193, v200, v194
	v_div_fixup_f32 v200, v193, v196, v154
	v_ashrrev_i32_e32 v193, 31, v192
	v_lshlrev_b64 v[192:193], s0, v[192:193]
	v_lshl_add_u64 v[202:203], v[192:193], 1, v[170:171]
	ds_read_b128 v[192:195], v165
	ds_read_b128 v[196:199], v169
	v_pk_mul_f32 v[208:209], v[74:75], v[200:201] op_sel_hi:[1,0]
	v_pk_mul_f32 v[210:211], v[76:77], v[200:201] op_sel_hi:[1,0]
	v_pk_mul_f32 v[204:205], v[80:81], v[200:201] op_sel_hi:[1,0]
	v_pk_mul_f32 v[206:207], v[78:79], v[200:201] op_sel_hi:[1,0]
	v_pk_mul_f32 v[210:211], v[136:137], v[210:211]
	v_pk_mul_f32 v[208:209], v[134:135], v[208:209]
	v_pk_mul_f32 v[206:207], v[138:139], v[206:207]
	v_pk_mul_f32 v[204:205], v[140:141], v[204:205]
	s_waitcnt lgkmcnt(0)
	v_pk_mul_f32 v[212:213], v[196:197], v[208:209]
	v_pk_mul_f32 v[214:215], v[198:199], v[210:211]
	v_pk_fma_f32 v[212:213], v[192:193], v[206:207], v[212:213] neg_lo:[0,0,1] neg_hi:[0,0,1]
	v_pk_fma_f32 v[214:215], v[194:195], v[204:205], v[214:215] neg_lo:[0,0,1] neg_hi:[0,0,1]
	v_pk_mul_f32 v[192:193], v[192:193], v[208:209]
	v_pk_mul_f32 v[194:195], v[194:195], v[210:211]
	v_pk_mul_f32 v[210:211], v[64:65], v[64:65]
	v_pk_fma_f32 v[198:199], v[198:199], v[204:205], v[194:195]
	v_pk_fma_f32 v[194:195], v[196:197], v[206:207], v[192:193]
	v_cvt_pk_bf16_f32 v192, v212, v213
	v_pk_mul_f32 v[212:213], v[62:63], v[62:63]
	v_cvt_pk_bf16_f32 v193, v214, v215
	v_mul_f32_e32 v165, v50, v50
	v_pk_mov_b32 v[214:215], v[212:213], v[210:211] op_sel:[1,0]
	v_mov_b32_e32 v213, v211
	v_pk_add_f32 v[210:211], v[214:215], v[212:213]
	v_pk_mul_f32 v[212:213], v[60:61], v[60:61]
	v_pk_mul_f32 v[214:215], v[58:59], v[58:59]
	v_mul_f32_e32 v169, v51, v51
	v_pk_mov_b32 v[216:217], v[214:215], v[212:213] op_sel:[1,0]
	v_mov_b32_e32 v215, v213
	v_pk_add_f32 v[212:213], v[216:217], v[214:215]
	v_pk_add_f32 v[210:211], v[210:211], v[210:211] op_sel:[0,1] op_sel_hi:[1,0]
	v_pk_add_f32 v[212:213], v[212:213], v[212:213] op_sel:[0,1] op_sel_hi:[1,0]
	v_mov_b32_e32 v211, v165
	v_mov_b32_e32 v213, v169
	v_pk_add_f32 v[210:211], v[210:211], v[212:213]
	v_mul_f32_e32 v212, v55, v55
	v_mul_f32_e32 v214, v52, v52
	v_pk_fma_f32 v[212:213], v[54:55], v[54:55], v[212:213] op_sel_hi:[1,1,0]
	v_mul_f32_e32 v216, v53, v53
	v_mov_b32_e32 v213, v214
	v_mul_f32_e32 v214, v57, v57
	v_pk_fma_f32 v[214:215], v[56:57], v[56:57], v[214:215] op_sel_hi:[1,1,0]
	v_cvt_pk_bf16_f32 v194, v194, v195
	v_cvt_pk_bf16_f32 v195, v198, v199
	global_store_dwordx4 v[202:203], v[192:195], off
	v_mov_b32_e32 v215, v216
	v_pk_add_f32 v[212:213], v[212:213], v[214:215]
	ds_read_b128 v[192:195], v180
	ds_read_b128 v[196:199], v181
	v_pk_add_f32 v[210:211], v[210:211], v[212:213]
	v_pk_mul_f32 v[204:205], v[72:73], v[200:201] op_sel_hi:[1,0]
	v_add_f32_e32 v165, v210, v211
	ds_bpermute_b32 v169, v190, v165
	v_pk_mul_f32 v[206:207], v[70:71], v[200:201] op_sel_hi:[1,0]
	v_pk_mul_f32 v[208:209], v[66:67], v[200:201] op_sel_hi:[1,0]
	v_pk_mul_f32 v[200:201], v[68:69], v[200:201] op_sel_hi:[1,0]
	v_pk_mul_f32 v[208:209], v[142:143], v[208:209]
	s_waitcnt lgkmcnt(0)
	v_add_f32_e32 v165, v165, v169
	ds_bpermute_b32 v169, v191, v165
	v_pk_mul_f32 v[200:201], v[144:145], v[200:201]
	v_pk_mul_f32 v[206:207], v[130:131], v[206:207]
	v_pk_mul_f32 v[204:205], v[132:133], v[204:205]
	v_pk_mul_f32 v[210:211], v[196:197], v[208:209]
	s_waitcnt lgkmcnt(0)
	v_add_f32_e32 v165, v165, v169
	v_fmamk_f32 v165, v165, 0x3c800000, v186
	v_mul_f32_e32 v169, 0x4f800000, v165
	v_cmp_gt_f32_e32 vcc, s96, v165
	v_pk_mul_f32 v[212:213], v[198:199], v[200:201]
	v_pk_fma_f32 v[210:211], v[192:193], v[206:207], v[210:211] neg_lo:[0,0,1] neg_hi:[0,0,1]
	v_cndmask_b32_e32 v165, v165, v169, vcc
	v_sqrt_f32_e32 v169, v165
	v_pk_fma_f32 v[212:213], v[194:195], v[204:205], v[212:213] neg_lo:[0,0,1] neg_hi:[0,0,1]
	v_pk_mul_f32 v[192:193], v[192:193], v[208:209]
	v_pk_mul_f32 v[194:195], v[194:195], v[200:201]
	s_nop 0
	v_pk_fma_f32 v[198:199], v[198:199], v[204:205], v[194:195]
	v_pk_fma_f32 v[194:195], v[196:197], v[206:207], v[192:193]
	v_cvt_pk_bf16_f32 v192, v210, v211
	v_cvt_pk_bf16_f32 v193, v212, v213
	s_nop 0
	v_cvt_pk_bf16_f32 v194, v194, v195
	v_add_u32_e32 v195, -1, v169
	v_fma_f32 v196, -v195, v169, v165
	v_cmp_ge_f32_e64 s[4:5], 0, v196
	v_add_u32_e32 v196, 1, v169
	s_nop 0
	v_cndmask_b32_e64 v195, v169, v195, s[4:5]
	v_fma_f32 v169, -v196, v169, v165
	v_cmp_lt_f32_e64 s[4:5], 0, v169
	s_nop 1
	v_cndmask_b32_e64 v169, v195, v196, s[4:5]
	v_mul_f32_e32 v195, 0x37800000, v169
	v_cndmask_b32_e32 v169, v169, v195, vcc
	v_cmp_class_f32_e32 vcc, v165, v187
	v_cvt_pk_bf16_f32 v195, v198, v199
	global_store_dwordx4 v[202:203], v[192:195], off offset:64
	s_nop 0
	v_cndmask_b32_e32 v165, v169, v165, vcc
	v_div_scale_f32 v169, s[4:5], v165, v165, v154
	v_rcp_f32_e32 v196, v169
	v_add_u32_e32 v192, 0x80, v168
	v_fma_f32 v193, -v169, v196, 1.0
	v_fmac_f32_e32 v196, v193, v196
	v_div_scale_f32 v193, vcc, v154, v165, v154
	v_mul_f32_e32 v194, v193, v196
	v_fma_f32 v195, -v169, v194, v193
	v_fmac_f32_e32 v194, v195, v196
	v_fma_f32 v169, -v169, v194, v193
	v_div_fmas_f32 v169, v169, v196, v194
	v_div_fixup_f32 v200, v169, v165, v154
	v_ashrrev_i32_e32 v193, 31, v192
	v_and_b32_e32 v169, 0x7c0, v192
	v_lshlrev_b64 v[194:195], s0, v[192:193]
	v_add_u32_e32 v165, v172, v169
	v_lshl_add_u64 v[202:203], v[194:195], 1, v[170:171]
	v_add_u32_e32 v169, v173, v169
	ds_read_b128 v[192:195], v165
	ds_read_b128 v[196:199], v169
	v_pk_mul_f32 v[208:209], v[58:59], v[200:201] op_sel_hi:[1,0]
	v_pk_mul_f32 v[210:211], v[60:61], v[200:201] op_sel_hi:[1,0]
	v_pk_mul_f32 v[204:205], v[64:65], v[200:201] op_sel_hi:[1,0]
	v_pk_mul_f32 v[206:207], v[62:63], v[200:201] op_sel_hi:[1,0]
	v_pk_mul_f32 v[210:211], v[136:137], v[210:211]
	v_pk_mul_f32 v[208:209], v[134:135], v[208:209]
	v_pk_mul_f32 v[206:207], v[138:139], v[206:207]
	v_pk_mul_f32 v[204:205], v[140:141], v[204:205]
	s_waitcnt lgkmcnt(0)
	v_pk_mul_f32 v[212:213], v[196:197], v[208:209]
	v_pk_mul_f32 v[214:215], v[198:199], v[210:211]
	v_pk_fma_f32 v[212:213], v[192:193], v[206:207], v[212:213] neg_lo:[0,0,1] neg_hi:[0,0,1]
	v_pk_fma_f32 v[214:215], v[194:195], v[204:205], v[214:215] neg_lo:[0,0,1] neg_hi:[0,0,1]
	v_pk_mul_f32 v[192:193], v[192:193], v[208:209]
	v_pk_mul_f32 v[194:195], v[194:195], v[210:211]
	v_pk_mul_f32 v[210:211], v[48:49], v[48:49]
	v_pk_fma_f32 v[198:199], v[198:199], v[204:205], v[194:195]
	v_pk_fma_f32 v[194:195], v[196:197], v[206:207], v[192:193]
	v_cvt_pk_bf16_f32 v192, v212, v213
	v_pk_mul_f32 v[212:213], v[46:47], v[46:47]
	v_cvt_pk_bf16_f32 v193, v214, v215
	v_cvt_pk_bf16_f32 v194, v194, v195
	v_cvt_pk_bf16_f32 v195, v198, v199
	global_store_dwordx4 v[202:203], v[192:195], off
	v_pk_mov_b32 v[214:215], v[212:213], v[210:211] op_sel:[1,0]
	v_mov_b32_e32 v213, v211
	v_pk_add_f32 v[210:211], v[214:215], v[212:213]
	v_pk_mul_f32 v[212:213], v[44:45], v[44:45]
	v_pk_mul_f32 v[214:215], v[42:43], v[42:43]
	v_pk_add_f32 v[210:211], v[210:211], v[210:211] op_sel:[0,1] op_sel_hi:[1,0]
	v_pk_mov_b32 v[216:217], v[214:215], v[212:213] op_sel:[1,0]
	v_mov_b32_e32 v215, v213
	v_pk_add_f32 v[212:213], v[216:217], v[214:215]
	v_mul_f32_e32 v214, v34, v34
	v_mul_f32_e32 v215, v35, v35
	v_pk_add_f32 v[212:213], v[212:213], v[212:213] op_sel:[0,1] op_sel_hi:[1,0]
	v_mov_b32_e32 v211, v214
	v_mov_b32_e32 v213, v215
	v_pk_add_f32 v[210:211], v[210:211], v[212:213]
	v_mul_f32_e32 v212, v39, v39
	v_mul_f32_e32 v214, v41, v41
	v_mul_f32_e32 v216, v36, v36
	v_mul_f32_e32 v217, v37, v37
	v_pk_fma_f32 v[212:213], v[38:39], v[38:39], v[212:213] op_sel_hi:[1,1,0]
	v_pk_fma_f32 v[214:215], v[40:41], v[40:41], v[214:215] op_sel_hi:[1,1,0]
	v_mov_b32_e32 v213, v216
	v_mov_b32_e32 v215, v217
	v_pk_add_f32 v[212:213], v[212:213], v[214:215]
	ds_read_b128 v[192:195], v174
	ds_read_b128 v[196:199], v175
	v_pk_add_f32 v[210:211], v[210:211], v[212:213]
	v_pk_mul_f32 v[204:205], v[56:57], v[200:201] op_sel_hi:[1,0]
	v_add_f32_e32 v214, v210, v211
	ds_bpermute_b32 v215, v190, v214
	v_pk_mul_f32 v[206:207], v[54:55], v[200:201] op_sel_hi:[1,0]
	v_pk_mul_f32 v[208:209], v[50:51], v[200:201] op_sel_hi:[1,0]
	v_pk_mul_f32 v[200:201], v[52:53], v[200:201] op_sel_hi:[1,0]
	v_pk_mul_f32 v[208:209], v[142:143], v[208:209]
	s_waitcnt lgkmcnt(0)
	v_add_f32_e32 v214, v214, v215
	ds_bpermute_b32 v215, v191, v214
	v_pk_mul_f32 v[200:201], v[144:145], v[200:201]
	v_pk_mul_f32 v[206:207], v[130:131], v[206:207]
	v_pk_mul_f32 v[204:205], v[132:133], v[204:205]
	v_pk_mul_f32 v[210:211], v[196:197], v[208:209]
	v_pk_mul_f32 v[212:213], v[198:199], v[200:201]
	v_pk_fma_f32 v[210:211], v[192:193], v[206:207], v[210:211] neg_lo:[0,0,1] neg_hi:[0,0,1]
	v_pk_fma_f32 v[212:213], v[194:195], v[204:205], v[212:213] neg_lo:[0,0,1] neg_hi:[0,0,1]
	v_pk_mul_f32 v[192:193], v[192:193], v[208:209]
	v_pk_mul_f32 v[194:195], v[194:195], v[200:201]
	s_nop 0
	v_pk_fma_f32 v[198:199], v[198:199], v[204:205], v[194:195]
	v_pk_fma_f32 v[194:195], v[196:197], v[206:207], v[192:193]
	s_waitcnt lgkmcnt(0)
	v_add_f32_e32 v192, v214, v215
	v_fmamk_f32 v192, v192, 0x3c800000, v186
	v_mul_f32_e32 v193, 0x4f800000, v192
	v_cmp_gt_f32_e32 vcc, s96, v192
	s_nop 1
	v_cndmask_b32_e32 v196, v192, v193, vcc
	v_sqrt_f32_e32 v197, v196
	v_cvt_pk_bf16_f32 v192, v210, v211
	v_cvt_pk_bf16_f32 v193, v212, v213
	v_cvt_pk_bf16_f32 v194, v194, v195
	s_nop 0
	v_add_u32_e32 v195, -1, v197
	v_fma_f32 v200, -v195, v197, v196
	v_cmp_ge_f32_e64 s[4:5], 0, v200
	v_add_u32_e32 v200, 1, v197
	s_nop 0
	v_cndmask_b32_e64 v195, v197, v195, s[4:5]
	v_fma_f32 v197, -v200, v197, v196
	v_cmp_lt_f32_e64 s[4:5], 0, v197
	s_nop 1
	v_cndmask_b32_e64 v195, v195, v200, s[4:5]
	v_mul_f32_e32 v197, 0x37800000, v195
	v_cndmask_b32_e32 v195, v195, v197, vcc
	v_cmp_class_f32_e32 vcc, v196, v187
	s_nop 1
	v_cndmask_b32_e32 v196, v195, v196, vcc
	v_div_scale_f32 v197, s[4:5], v196, v196, v154
	v_rcp_f32_e32 v200, v197
	v_cvt_pk_bf16_f32 v195, v198, v199
	global_store_dwordx4 v[202:203], v[192:195], off offset:64
	s_nop 1
	v_fma_f32 v193, -v197, v200, 1.0
	v_fmac_f32_e32 v200, v193, v200
	v_div_scale_f32 v193, vcc, v154, v196, v154
	v_mul_f32_e32 v194, v193, v200
	v_fma_f32 v195, -v197, v194, v193
	v_fmac_f32_e32 v194, v195, v200
	v_fma_f32 v193, -v197, v194, v193
	v_add_u32_e32 v192, 0x90, v168
	v_div_fmas_f32 v193, v193, v200, v194
	v_div_fixup_f32 v200, v193, v196, v154
	v_ashrrev_i32_e32 v193, 31, v192
	v_lshlrev_b64 v[192:193], s0, v[192:193]
	v_lshl_add_u64 v[202:203], v[192:193], 1, v[170:171]
	ds_read_b128 v[192:195], v165
	ds_read_b128 v[196:199], v169
	v_pk_mul_f32 v[208:209], v[42:43], v[200:201] op_sel_hi:[1,0]
	v_pk_mul_f32 v[210:211], v[44:45], v[200:201] op_sel_hi:[1,0]
	v_pk_mul_f32 v[204:205], v[48:49], v[200:201] op_sel_hi:[1,0]
	v_pk_mul_f32 v[206:207], v[46:47], v[200:201] op_sel_hi:[1,0]
	v_pk_mul_f32 v[210:211], v[136:137], v[210:211]
	v_pk_mul_f32 v[208:209], v[134:135], v[208:209]
	v_pk_mul_f32 v[206:207], v[138:139], v[206:207]
	v_pk_mul_f32 v[204:205], v[140:141], v[204:205]
	s_waitcnt lgkmcnt(0)
	v_pk_mul_f32 v[212:213], v[196:197], v[208:209]
	v_pk_mul_f32 v[214:215], v[198:199], v[210:211]
	v_pk_fma_f32 v[212:213], v[192:193], v[206:207], v[212:213] neg_lo:[0,0,1] neg_hi:[0,0,1]
	v_pk_fma_f32 v[214:215], v[194:195], v[204:205], v[214:215] neg_lo:[0,0,1] neg_hi:[0,0,1]
	v_pk_mul_f32 v[192:193], v[192:193], v[208:209]
	v_pk_mul_f32 v[194:195], v[194:195], v[210:211]
	v_pk_mul_f32 v[210:211], v[32:33], v[32:33]
	v_pk_fma_f32 v[198:199], v[198:199], v[204:205], v[194:195]
	v_pk_fma_f32 v[194:195], v[196:197], v[206:207], v[192:193]
	v_cvt_pk_bf16_f32 v192, v212, v213
	v_pk_mul_f32 v[212:213], v[30:31], v[30:31]
	v_cvt_pk_bf16_f32 v193, v214, v215
	v_cvt_pk_bf16_f32 v194, v194, v195
	v_cvt_pk_bf16_f32 v195, v198, v199
	global_store_dwordx4 v[202:203], v[192:195], off
	v_pk_mov_b32 v[214:215], v[212:213], v[210:211] op_sel:[1,0]
	v_mov_b32_e32 v213, v211
	v_pk_add_f32 v[210:211], v[214:215], v[212:213]
	v_pk_mul_f32 v[212:213], v[28:29], v[28:29]
	v_pk_mul_f32 v[214:215], v[26:27], v[26:27]
	v_pk_add_f32 v[210:211], v[210:211], v[210:211] op_sel:[0,1] op_sel_hi:[1,0]
	v_pk_mov_b32 v[216:217], v[214:215], v[212:213] op_sel:[1,0]
	v_mov_b32_e32 v215, v213
	v_pk_add_f32 v[212:213], v[216:217], v[214:215]
	v_mul_f32_e32 v214, v18, v18
	v_mul_f32_e32 v215, v19, v19
	v_pk_add_f32 v[212:213], v[212:213], v[212:213] op_sel:[0,1] op_sel_hi:[1,0]
	v_mov_b32_e32 v211, v214
	v_mov_b32_e32 v213, v215
	v_pk_add_f32 v[210:211], v[210:211], v[212:213]
	v_mul_f32_e32 v212, v23, v23
	v_mul_f32_e32 v214, v25, v25
	v_mul_f32_e32 v216, v20, v20
	v_mul_f32_e32 v217, v21, v21
	v_pk_fma_f32 v[212:213], v[22:23], v[22:23], v[212:213] op_sel_hi:[1,1,0]
	v_pk_fma_f32 v[214:215], v[24:25], v[24:25], v[214:215] op_sel_hi:[1,1,0]
	v_mov_b32_e32 v213, v216
	v_mov_b32_e32 v215, v217
	v_pk_add_f32 v[212:213], v[212:213], v[214:215]
	ds_read_b128 v[192:195], v176
	ds_read_b128 v[196:199], v177
	v_pk_add_f32 v[210:211], v[210:211], v[212:213]
	v_pk_mul_f32 v[204:205], v[40:41], v[200:201] op_sel_hi:[1,0]
	v_add_f32_e32 v214, v210, v211
	ds_bpermute_b32 v215, v190, v214
	v_pk_mul_f32 v[206:207], v[38:39], v[200:201] op_sel_hi:[1,0]
	v_pk_mul_f32 v[208:209], v[34:35], v[200:201] op_sel_hi:[1,0]
	v_pk_mul_f32 v[200:201], v[36:37], v[200:201] op_sel_hi:[1,0]
	v_pk_mul_f32 v[208:209], v[142:143], v[208:209]
	s_waitcnt lgkmcnt(0)
	v_add_f32_e32 v214, v214, v215
	ds_bpermute_b32 v215, v191, v214
	v_pk_mul_f32 v[200:201], v[144:145], v[200:201]
	v_pk_mul_f32 v[206:207], v[130:131], v[206:207]
	v_pk_mul_f32 v[204:205], v[132:133], v[204:205]
	v_pk_mul_f32 v[210:211], v[196:197], v[208:209]
	v_pk_mul_f32 v[212:213], v[198:199], v[200:201]
	v_pk_fma_f32 v[210:211], v[192:193], v[206:207], v[210:211] neg_lo:[0,0,1] neg_hi:[0,0,1]
	v_pk_fma_f32 v[212:213], v[194:195], v[204:205], v[212:213] neg_lo:[0,0,1] neg_hi:[0,0,1]
	v_pk_mul_f32 v[192:193], v[192:193], v[208:209]
	v_pk_mul_f32 v[194:195], v[194:195], v[200:201]
	s_nop 0
	v_pk_fma_f32 v[198:199], v[198:199], v[204:205], v[194:195]
	v_pk_fma_f32 v[194:195], v[196:197], v[206:207], v[192:193]
	s_waitcnt lgkmcnt(0)
	v_add_f32_e32 v192, v214, v215
	v_fmamk_f32 v192, v192, 0x3c800000, v186
	v_mul_f32_e32 v193, 0x4f800000, v192
	v_cmp_gt_f32_e32 vcc, s96, v192
	s_nop 1
	v_cndmask_b32_e32 v196, v192, v193, vcc
	v_sqrt_f32_e32 v197, v196
	v_cvt_pk_bf16_f32 v192, v210, v211
	v_cvt_pk_bf16_f32 v193, v212, v213
	v_cvt_pk_bf16_f32 v194, v194, v195
	s_nop 0
	v_add_u32_e32 v195, -1, v197
	v_fma_f32 v200, -v195, v197, v196
	v_cmp_ge_f32_e64 s[4:5], 0, v200
	v_add_u32_e32 v200, 1, v197
	s_nop 0
	v_cndmask_b32_e64 v195, v197, v195, s[4:5]
	v_fma_f32 v197, -v200, v197, v196
	v_cmp_lt_f32_e64 s[4:5], 0, v197
	s_nop 1
	v_cndmask_b32_e64 v195, v195, v200, s[4:5]
	v_mul_f32_e32 v197, 0x37800000, v195
	v_cndmask_b32_e32 v195, v195, v197, vcc
	v_cmp_class_f32_e32 vcc, v196, v187
	s_nop 1
	v_cndmask_b32_e32 v196, v195, v196, vcc
	v_div_scale_f32 v197, s[4:5], v196, v196, v154
	v_rcp_f32_e32 v200, v197
	v_cvt_pk_bf16_f32 v195, v198, v199
	global_store_dwordx4 v[202:203], v[192:195], off offset:64
	s_nop 1
	v_fma_f32 v193, -v197, v200, 1.0
	v_fmac_f32_e32 v200, v193, v200
	v_div_scale_f32 v193, vcc, v154, v196, v154
	v_mul_f32_e32 v194, v193, v200
	v_fma_f32 v195, -v197, v194, v193
	v_fmac_f32_e32 v194, v195, v200
	v_fma_f32 v193, -v197, v194, v193
	v_add_u32_e32 v192, 0xa0, v168
	v_div_fmas_f32 v193, v193, v200, v194
	v_div_fixup_f32 v200, v193, v196, v154
	v_ashrrev_i32_e32 v193, 31, v192
	v_lshlrev_b64 v[192:193], s0, v[192:193]
	v_lshl_add_u64 v[202:203], v[192:193], 1, v[170:171]
	ds_read_b128 v[192:195], v165
	ds_read_b128 v[196:199], v169
	v_pk_mul_f32 v[208:209], v[26:27], v[200:201] op_sel_hi:[1,0]
	v_pk_mul_f32 v[210:211], v[28:29], v[200:201] op_sel_hi:[1,0]
	v_pk_mul_f32 v[204:205], v[32:33], v[200:201] op_sel_hi:[1,0]
	v_pk_mul_f32 v[206:207], v[30:31], v[200:201] op_sel_hi:[1,0]
	v_pk_mul_f32 v[210:211], v[136:137], v[210:211]
	v_pk_mul_f32 v[208:209], v[134:135], v[208:209]
	v_pk_mul_f32 v[206:207], v[138:139], v[206:207]
	v_pk_mul_f32 v[204:205], v[140:141], v[204:205]
	s_waitcnt lgkmcnt(0)
	v_pk_mul_f32 v[212:213], v[196:197], v[208:209]
	v_pk_mul_f32 v[214:215], v[198:199], v[210:211]
	v_pk_fma_f32 v[212:213], v[192:193], v[206:207], v[212:213] neg_lo:[0,0,1] neg_hi:[0,0,1]
	v_pk_fma_f32 v[214:215], v[194:195], v[204:205], v[214:215] neg_lo:[0,0,1] neg_hi:[0,0,1]
	v_pk_mul_f32 v[192:193], v[192:193], v[208:209]
	v_pk_mul_f32 v[194:195], v[194:195], v[210:211]
	v_pk_mul_f32 v[210:211], v[16:17], v[16:17]
	v_pk_fma_f32 v[198:199], v[198:199], v[204:205], v[194:195]
	v_pk_fma_f32 v[194:195], v[196:197], v[206:207], v[192:193]
	v_cvt_pk_bf16_f32 v192, v212, v213
	v_pk_mul_f32 v[212:213], v[14:15], v[14:15]
	v_cvt_pk_bf16_f32 v193, v214, v215
	v_cvt_pk_bf16_f32 v194, v194, v195
	v_cvt_pk_bf16_f32 v195, v198, v199
	global_store_dwordx4 v[202:203], v[192:195], off
	v_pk_mov_b32 v[214:215], v[212:213], v[210:211] op_sel:[1,0]
	v_mov_b32_e32 v213, v211
	v_pk_add_f32 v[210:211], v[214:215], v[212:213]
	v_pk_mul_f32 v[212:213], v[12:13], v[12:13]
	v_pk_mul_f32 v[214:215], v[10:11], v[10:11]
	v_pk_add_f32 v[210:211], v[210:211], v[210:211] op_sel:[0,1] op_sel_hi:[1,0]
	v_pk_mov_b32 v[216:217], v[214:215], v[212:213] op_sel:[1,0]
	v_mov_b32_e32 v215, v213
	v_pk_add_f32 v[212:213], v[216:217], v[214:215]
	v_mul_f32_e32 v214, v2, v2
	v_mul_f32_e32 v215, v3, v3
	v_pk_add_f32 v[212:213], v[212:213], v[212:213] op_sel:[0,1] op_sel_hi:[1,0]
	v_mov_b32_e32 v211, v214
	v_mov_b32_e32 v213, v215
	v_pk_add_f32 v[210:211], v[210:211], v[212:213]
	v_mul_f32_e32 v212, v7, v7
	v_mul_f32_e32 v214, v9, v9
	v_mul_f32_e32 v216, v4, v4
	v_mul_f32_e32 v217, v5, v5
	v_pk_fma_f32 v[212:213], v[6:7], v[6:7], v[212:213] op_sel_hi:[1,1,0]
	v_pk_fma_f32 v[214:215], v[8:9], v[8:9], v[214:215] op_sel_hi:[1,1,0]
	v_mov_b32_e32 v213, v216
	v_mov_b32_e32 v215, v217
	v_pk_add_f32 v[212:213], v[212:213], v[214:215]
	ds_read_b128 v[192:195], v178
	ds_read_b128 v[196:199], v179
	v_pk_add_f32 v[210:211], v[210:211], v[212:213]
	v_pk_mul_f32 v[208:209], v[18:19], v[200:201] op_sel_hi:[1,0]
	v_add_f32_e32 v214, v210, v211
	ds_bpermute_b32 v190, v190, v214
	v_pk_mul_f32 v[204:205], v[24:25], v[200:201] op_sel_hi:[1,0]
	v_pk_mul_f32 v[206:207], v[22:23], v[200:201] op_sel_hi:[1,0]
	v_pk_mul_f32 v[200:201], v[20:21], v[200:201] op_sel_hi:[1,0]
	v_pk_mul_f32 v[208:209], v[142:143], v[208:209]
	s_waitcnt lgkmcnt(0)
	v_add_f32_e32 v214, v214, v190
	ds_bpermute_b32 v215, v191, v214
	v_pk_mul_f32 v[206:207], v[130:131], v[206:207]
	v_pk_mul_f32 v[200:201], v[144:145], v[200:201]
	v_pk_mul_f32 v[210:211], v[196:197], v[208:209]
	v_pk_mul_f32 v[204:205], v[132:133], v[204:205]
	v_pk_mul_f32 v[212:213], v[198:199], v[200:201]
	v_pk_fma_f32 v[210:211], v[192:193], v[206:207], v[210:211] neg_lo:[0,0,1] neg_hi:[0,0,1]
	v_pk_mul_f32 v[190:191], v[192:193], v[208:209]
	v_pk_mul_f32 v[192:193], v[194:195], v[200:201]
	v_pk_fma_f32 v[212:213], v[194:195], v[204:205], v[212:213] neg_lo:[0,0,1] neg_hi:[0,0,1]
	v_pk_fma_f32 v[194:195], v[198:199], v[204:205], v[192:193]
	v_pk_fma_f32 v[192:193], v[196:197], v[206:207], v[190:191]
	s_waitcnt lgkmcnt(0)
	v_add_f32_e32 v190, v214, v215
	v_fmamk_f32 v190, v190, 0x3c800000, v186
	v_mul_f32_e32 v191, 0x4f800000, v190
	v_cmp_gt_f32_e32 vcc, s96, v190
	s_nop 1
	v_cndmask_b32_e32 v196, v190, v191, vcc
	v_sqrt_f32_e32 v197, v196
	v_cvt_pk_bf16_f32 v190, v210, v211
	v_cvt_pk_bf16_f32 v191, v212, v213
	v_cvt_pk_bf16_f32 v192, v192, v193
	s_nop 0
	v_add_u32_e32 v193, -1, v197
	v_fma_f32 v198, -v193, v197, v196
	v_cmp_ge_f32_e64 s[4:5], 0, v198
	v_add_u32_e32 v198, 1, v197
	s_nop 0
	v_cndmask_b32_e64 v193, v197, v193, s[4:5]
	v_fma_f32 v197, -v198, v197, v196
	v_cmp_lt_f32_e64 s[4:5], 0, v197
	s_nop 1
	v_cndmask_b32_e64 v193, v193, v198, s[4:5]
	v_mul_f32_e32 v197, 0x37800000, v193
	v_cndmask_b32_e32 v193, v193, v197, vcc
	v_cmp_class_f32_e32 vcc, v196, v187
	s_nop 1
	v_cndmask_b32_e32 v196, v193, v196, vcc
	v_div_scale_f32 v197, s[4:5], v196, v196, v154
	v_rcp_f32_e32 v198, v197
	v_cvt_pk_bf16_f32 v193, v194, v195
	global_store_dwordx4 v[202:203], v[190:193], off offset:64
	s_nop 1
	v_fma_f32 v191, -v197, v198, 1.0
	v_fmac_f32_e32 v198, v191, v198
	v_div_scale_f32 v191, vcc, v154, v196, v154
	v_mul_f32_e32 v192, v191, v198
	v_fma_f32 v193, -v197, v192, v191
	v_fmac_f32_e32 v192, v193, v198
	v_fma_f32 v191, -v197, v192, v191
	v_add_u32_e32 v190, 0xb0, v168
	v_div_fmas_f32 v191, v191, v198, v192
	v_div_fixup_f32 v154, v191, v196, v154
	v_ashrrev_i32_e32 v191, 31, v190
	v_lshlrev_b64 v[190:191], s0, v[190:191]
	v_lshl_add_u64 v[170:171], v[190:191], 1, v[170:171]
	ds_read_b128 v[190:193], v165
	ds_read_b128 v[194:197], v169
	v_pk_mul_f32 v[198:199], v[16:17], v[154:155] op_sel_hi:[1,0]
	v_pk_mul_f32 v[200:201], v[14:15], v[154:155] op_sel_hi:[1,0]
	v_pk_mul_f32 v[140:141], v[140:141], v[198:199]
	v_pk_mul_f32 v[138:139], v[138:139], v[200:201]
	v_pk_mul_f32 v[198:199], v[10:11], v[154:155] op_sel_hi:[1,0]
	v_pk_mul_f32 v[200:201], v[12:13], v[154:155] op_sel_hi:[1,0]
	v_pk_mul_f32 v[134:135], v[134:135], v[198:199]
	v_pk_mul_f32 v[136:137], v[136:137], v[200:201]
	s_waitcnt lgkmcnt(0)
	v_pk_mul_f32 v[198:199], v[194:195], v[134:135]
	v_pk_mul_f32 v[200:201], v[196:197], v[136:137]
	v_pk_mul_f32 v[134:135], v[190:191], v[134:135]
	v_pk_mul_f32 v[136:137], v[192:193], v[136:137]
	v_pk_fma_f32 v[200:201], v[192:193], v[140:141], v[200:201] neg_lo:[0,0,1] neg_hi:[0,0,1]
	v_pk_fma_f32 v[140:141], v[196:197], v[140:141], v[136:137]
	v_pk_fma_f32 v[136:137], v[194:195], v[138:139], v[134:135]
	v_pk_fma_f32 v[198:199], v[190:191], v[138:139], v[198:199] neg_lo:[0,0,1] neg_hi:[0,0,1]
	v_pk_mul_f32 v[190:191], v[8:9], v[154:155] op_sel_hi:[1,0]
	v_cvt_pk_bf16_f32 v134, v198, v199
	v_cvt_pk_bf16_f32 v135, v200, v201
	v_cvt_pk_bf16_f32 v136, v136, v137
	v_cvt_pk_bf16_f32 v137, v140, v141
	global_store_dwordx4 v[170:171], v[134:137], off
	ds_read_b128 v[134:137], v180
	ds_read_b128 v[138:141], v181
	v_pk_mul_f32 v[192:193], v[6:7], v[154:155] op_sel_hi:[1,0]
	v_pk_mul_f32 v[132:133], v[132:133], v[190:191]
	v_pk_mul_f32 v[130:131], v[130:131], v[192:193]
	v_pk_mul_f32 v[190:191], v[2:3], v[154:155] op_sel_hi:[1,0]
	v_pk_mul_f32 v[192:193], v[4:5], v[154:155] op_sel_hi:[1,0]
	v_pk_mul_f32 v[142:143], v[142:143], v[190:191]
	v_pk_mul_f32 v[144:145], v[144:145], v[192:193]
	s_waitcnt lgkmcnt(0)
	v_pk_mul_f32 v[190:191], v[138:139], v[142:143]
	v_pk_mul_f32 v[192:193], v[140:141], v[144:145]
	v_pk_fma_f32 v[190:191], v[134:135], v[130:131], v[190:191] neg_lo:[0,0,1] neg_hi:[0,0,1]
	v_pk_fma_f32 v[192:193], v[136:137], v[132:133], v[192:193] neg_lo:[0,0,1] neg_hi:[0,0,1]
	v_pk_mul_f32 v[134:135], v[134:135], v[142:143]
	v_pk_mul_f32 v[136:137], v[136:137], v[144:145]
	s_nop 0
	v_pk_fma_f32 v[136:137], v[140:141], v[132:133], v[136:137]
	v_pk_fma_f32 v[132:133], v[138:139], v[130:131], v[134:135]
	v_cvt_pk_bf16_f32 v130, v190, v191
	v_cvt_pk_bf16_f32 v131, v192, v193
	s_nop 0
	v_cvt_pk_bf16_f32 v132, v132, v133
	v_cvt_pk_bf16_f32 v133, v136, v137
